# strategy 9 loop-edge edit: v054 + the K-loops' loop-end SALU (counter, pointer bumps, exit compare) moved from behind the closing barrier into the last MFMA block's shadow
# baseline (speedup 1.0000x reference)
.LBB0_323:
	s_add_u32 s26, s24, 0xfffc0080
	s_addc_u32 s27, s25, -1
	s_add_i32 s36, 0, 0x10000
	s_cmp_eq_u32 s21, 12
	s_cselect_b32 s57, s17, s27
	s_cselect_b32 s56, s16, s26
	v_add_u32_e32 v142, s36, v161
	s_cselect_b32 s27, s19, s15
	s_cselect_b32 s26, s18, s13
	s_add_i32 s38, 0, 0x14000
	ds_read_b128 v[144:147], v142
	ds_read_b128 v[148:151], v142 offset:1024
	ds_read_b128 v[152:155], v142 offset:2048
	ds_read_b128 v[178:181], v142 offset:3072
	v_add_u32_e32 v142, s38, v161
	ds_read_b128 v[182:185], v142
	ds_read_b128 v[186:189], v142 offset:1024
	ds_read_b128 v[190:193], v142 offset:2048
	ds_read_b128 v[194:197], v142 offset:3072
	v_lshl_add_u64 v[156:157], s[24:25], 0, v[140:141]
	s_add_i32 m0, s68, 0xc000
	ds_read_b128 v[198:201], v177
	ds_read_b128 v[202:205], v177 offset:1024
	ds_read_b128 v[206:209], v177 offset:2048
	ds_read_b128 v[210:213], v177 offset:3072
	ds_read_b128 v[214:217], v177 offset:4096
	ds_read_b128 v[222:225], v177 offset:5120
	ds_read_b128 v[226:229], v177 offset:6144
	ds_read_b128 v[230:233], v177 offset:7168
	global_load_lds_dwordx4 v[156:157], off
	v_lshl_add_u64 v[156:157], s[24:25], 0, v[138:139]
	s_add_i32 m0, s68, 0xe000
	s_nop 0
	global_load_lds_dwordx4 v[156:157], off
	s_waitcnt vmcnt(8)
	s_waitcnt lgkmcnt(0)
	s_barrier
	v_mfma_i32_16x16x64_i8 v[126:129], v[144:147], v[198:201], v[126:129]
	v_mfma_i32_16x16x64_i8 v[118:121], v[152:155], v[198:201], v[118:121]
	v_mfma_i32_16x16x64_i8 v[110:113], v[144:147], v[206:209], v[110:113]
	v_mfma_i32_16x16x64_i8 v[102:105], v[152:155], v[206:209], v[102:105]
	v_mfma_i32_16x16x64_i8 v[94:97], v[144:147], v[214:217], v[94:97]
	v_mfma_i32_16x16x64_i8 v[86:89], v[152:155], v[214:217], v[86:89]
	v_mfma_i32_16x16x64_i8 v[78:81], v[144:147], v[226:229], v[78:81]
	v_mfma_i32_16x16x64_i8 v[70:73], v[152:155], v[226:229], v[70:73]
	v_mfma_i32_16x16x64_i8 v[126:129], v[148:151], v[202:205], v[126:129]
	v_mfma_i32_16x16x64_i8 v[118:121], v[178:181], v[202:205], v[118:121]
	v_mfma_i32_16x16x64_i8 v[110:113], v[148:151], v[210:213], v[110:113]
	v_mfma_i32_16x16x64_i8 v[102:105], v[178:181], v[210:213], v[102:105]
	v_mfma_i32_16x16x64_i8 v[94:97], v[148:151], v[222:225], v[94:97]
	v_mfma_i32_16x16x64_i8 v[86:89], v[178:181], v[222:225], v[86:89]
	v_mfma_i32_16x16x64_i8 v[78:81], v[148:151], v[230:233], v[78:81]
	v_mfma_i32_16x16x64_i8 v[70:73], v[178:181], v[230:233], v[70:73]
	v_mfma_i32_16x16x64_i8 v[122:125], v[182:185], v[198:201], v[122:125]
	v_mfma_i32_16x16x64_i8 v[114:117], v[190:193], v[198:201], v[114:117]
	v_mfma_i32_16x16x64_i8 v[106:109], v[182:185], v[206:209], v[106:109]
	v_mfma_i32_16x16x64_i8 v[98:101], v[190:193], v[206:209], v[98:101]
	v_mfma_i32_16x16x64_i8 v[90:93], v[182:185], v[214:217], v[90:93]
	v_mfma_i32_16x16x64_i8 v[82:85], v[190:193], v[214:217], v[82:85]
	v_mfma_i32_16x16x64_i8 v[74:77], v[182:185], v[226:229], v[74:77]
	v_mfma_i32_16x16x64_i8 v[66:69], v[190:193], v[226:229], v[66:69]
	v_mfma_i32_16x16x64_i8 v[122:125], v[186:189], v[202:205], v[122:125]
	v_mfma_i32_16x16x64_i8 v[114:117], v[194:197], v[202:205], v[114:117]
	v_mfma_i32_16x16x64_i8 v[106:109], v[186:189], v[210:213], v[106:109]
	v_mfma_i32_16x16x64_i8 v[98:101], v[194:197], v[210:213], v[98:101]
	v_mfma_i32_16x16x64_i8 v[90:93], v[186:189], v[222:225], v[90:93]
	v_mfma_i32_16x16x64_i8 v[82:85], v[194:197], v[222:225], v[82:85]
	v_mfma_i32_16x16x64_i8 v[74:77], v[186:189], v[230:233], v[74:77]
	v_mfma_i32_16x16x64_i8 v[66:69], v[194:197], v[230:233], v[66:69]
	s_barrier
	s_add_i32 s36, s36, s23
	v_lshl_add_u64 v[156:157], s[26:27], 0, v[162:163]
	s_mov_b32 m0, s36
	ds_read_b128 v[198:201], v177 offset:16384
	ds_read_b128 v[202:205], v177 offset:17408
	ds_read_b128 v[206:209], v177 offset:18432
	ds_read_b128 v[210:213], v177 offset:19456
	ds_read_b128 v[214:217], v177 offset:20480
	ds_read_b128 v[222:225], v177 offset:21504
	ds_read_b128 v[226:229], v177 offset:22528
	ds_read_b128 v[230:233], v177 offset:23552
	global_load_lds_dwordx4 v[156:157], off
	s_add_i32 m0, s36, 0x2000
	s_add_u32 s36, s26, 0x80000
	v_lshl_add_u64 v[174:175], s[26:27], 0, v[134:135]
	s_addc_u32 s37, s27, 0
	s_add_i32 s38, s38, s23
	global_load_lds_dwordx4 v[174:175], off
	v_lshl_add_u64 v[234:235], s[36:37], 0, v[162:163]
	s_mov_b32 m0, s38
	v_lshl_add_u64 v[236:237], s[56:57], 0, v[132:133]
	global_load_lds_dwordx4 v[234:235], off
	v_lshl_add_u64 v[234:235], s[36:37], 0, v[134:135]
	s_add_i32 m0, s38, 0x2000
	s_nop 0
	global_load_lds_dwordx4 v[234:235], off
	v_lshl_add_u64 v[234:235], s[56:57], 0, v[130:131]
	s_mov_b32 m0, s68
	s_nop 0
	global_load_lds_dwordx4 v[234:235], off
	s_mov_b32 m0, s69
	s_nop 0
	global_load_lds_dwordx4 v[236:237], off
	s_waitcnt vmcnt(8)
	s_waitcnt lgkmcnt(0)
	s_barrier
	v_mfma_i32_16x16x64_i8 v[62:65], v[144:147], v[198:201], v[62:65]
	v_mfma_i32_16x16x64_i8 v[54:57], v[152:155], v[198:201], v[54:57]
	v_mfma_i32_16x16x64_i8 v[46:49], v[144:147], v[206:209], v[46:49]
	v_mfma_i32_16x16x64_i8 v[38:41], v[152:155], v[206:209], v[38:41]
	v_mfma_i32_16x16x64_i8 v[30:33], v[144:147], v[214:217], v[30:33]
	v_mfma_i32_16x16x64_i8 v[22:25], v[152:155], v[214:217], v[22:25]
	v_mfma_i32_16x16x64_i8 v[14:17], v[144:147], v[226:229], v[14:17]
	v_mfma_i32_16x16x64_i8 v[6:9], v[152:155], v[226:229], v[6:9]
	v_mfma_i32_16x16x64_i8 v[62:65], v[148:151], v[202:205], v[62:65]
	v_mfma_i32_16x16x64_i8 v[54:57], v[178:181], v[202:205], v[54:57]
	v_mfma_i32_16x16x64_i8 v[46:49], v[148:151], v[210:213], v[46:49]
	v_mfma_i32_16x16x64_i8 v[38:41], v[178:181], v[210:213], v[38:41]
	v_mfma_i32_16x16x64_i8 v[30:33], v[148:151], v[222:225], v[30:33]
	v_mfma_i32_16x16x64_i8 v[22:25], v[178:181], v[222:225], v[22:25]
	v_mfma_i32_16x16x64_i8 v[14:17], v[148:151], v[230:233], v[14:17]
	v_mfma_i32_16x16x64_i8 v[6:9], v[178:181], v[230:233], v[6:9]
	v_mfma_i32_16x16x64_i8 v[58:61], v[182:185], v[198:201], v[58:61]
	v_mfma_i32_16x16x64_i8 v[50:53], v[190:193], v[198:201], v[50:53]
	v_mfma_i32_16x16x64_i8 v[42:45], v[182:185], v[206:209], v[42:45]
	v_mfma_i32_16x16x64_i8 v[34:37], v[190:193], v[206:209], v[34:37]
	v_mfma_i32_16x16x64_i8 v[26:29], v[182:185], v[214:217], v[26:29]
	v_mfma_i32_16x16x64_i8 v[18:21], v[190:193], v[214:217], v[18:21]
	v_mfma_i32_16x16x64_i8 v[10:13], v[182:185], v[226:229], v[10:13]
	v_mfma_i32_16x16x64_i8 v[2:5], v[190:193], v[226:229], v[2:5]
	v_mfma_i32_16x16x64_i8 v[58:61], v[186:189], v[202:205], v[58:61]
	v_mfma_i32_16x16x64_i8 v[50:53], v[194:197], v[202:205], v[50:53]
	v_mfma_i32_16x16x64_i8 v[42:45], v[186:189], v[210:213], v[42:45]
	v_mfma_i32_16x16x64_i8 v[34:37], v[194:197], v[210:213], v[34:37]
	v_mfma_i32_16x16x64_i8 v[26:29], v[186:189], v[222:225], v[26:29]
	v_mfma_i32_16x16x64_i8 v[18:21], v[194:197], v[222:225], v[18:21]
	v_mfma_i32_16x16x64_i8 v[10:13], v[186:189], v[230:233], v[10:13]
	v_mfma_i32_16x16x64_i8 v[2:5], v[194:197], v[230:233], v[2:5]
	s_barrier
	s_add_i32 s38, 0, 0x18000
	v_add_u32_e32 v142, s38, v161
	s_add_i32 s39, 0, 0x1c000
	ds_read_b128 v[144:147], v142
	ds_read_b128 v[148:151], v142 offset:1024
	ds_read_b128 v[152:155], v142 offset:2048
	ds_read_b128 v[178:181], v142 offset:3072
	v_add_u32_e32 v142, s39, v161
	ds_read_b128 v[182:185], v142
	ds_read_b128 v[186:189], v142 offset:1024
	ds_read_b128 v[190:193], v142 offset:2048
	ds_read_b128 v[194:197], v142 offset:3072
	s_add_u32 s36, s56, 0x40000
	s_addc_u32 s37, s57, 0
	s_mov_b32 m0, s70
	v_lshl_add_u64 v[238:239], s[36:37], 0, v[130:131]
	ds_read_b128 v[198:201], v177 offset:32768
	ds_read_b128 v[202:205], v177 offset:33792
	ds_read_b128 v[206:209], v177 offset:34816
	ds_read_b128 v[210:213], v177 offset:35840
	ds_read_b128 v[214:217], v177 offset:36864
	ds_read_b128 v[222:225], v177 offset:37888
	ds_read_b128 v[226:229], v177 offset:38912
	ds_read_b128 v[230:233], v177 offset:39936
	global_load_lds_dwordx4 v[238:239], off
	v_lshl_add_u64 v[238:239], s[36:37], 0, v[132:133]
	s_mov_b32 m0, s71
	s_nop 0
	global_load_lds_dwordx4 v[238:239], off
	s_waitcnt vmcnt(8)
	s_waitcnt lgkmcnt(0)
	s_barrier
	v_mfma_i32_16x16x64_i8 v[126:129], v[144:147], v[198:201], v[126:129]
	v_mfma_i32_16x16x64_i8 v[118:121], v[152:155], v[198:201], v[118:121]
	v_mfma_i32_16x16x64_i8 v[110:113], v[144:147], v[206:209], v[110:113]
	v_mfma_i32_16x16x64_i8 v[102:105], v[152:155], v[206:209], v[102:105]
	v_mfma_i32_16x16x64_i8 v[94:97], v[144:147], v[214:217], v[94:97]
	v_mfma_i32_16x16x64_i8 v[86:89], v[152:155], v[214:217], v[86:89]
	v_mfma_i32_16x16x64_i8 v[78:81], v[144:147], v[226:229], v[78:81]
	v_mfma_i32_16x16x64_i8 v[70:73], v[152:155], v[226:229], v[70:73]
	v_mfma_i32_16x16x64_i8 v[126:129], v[148:151], v[202:205], v[126:129]
	v_mfma_i32_16x16x64_i8 v[118:121], v[178:181], v[202:205], v[118:121]
	v_mfma_i32_16x16x64_i8 v[110:113], v[148:151], v[210:213], v[110:113]
	v_mfma_i32_16x16x64_i8 v[102:105], v[178:181], v[210:213], v[102:105]
	v_mfma_i32_16x16x64_i8 v[94:97], v[148:151], v[222:225], v[94:97]
	v_mfma_i32_16x16x64_i8 v[86:89], v[178:181], v[222:225], v[86:89]
	v_mfma_i32_16x16x64_i8 v[78:81], v[148:151], v[230:233], v[78:81]
	v_mfma_i32_16x16x64_i8 v[70:73], v[178:181], v[230:233], v[70:73]
	v_mfma_i32_16x16x64_i8 v[122:125], v[182:185], v[198:201], v[122:125]
	v_mfma_i32_16x16x64_i8 v[114:117], v[190:193], v[198:201], v[114:117]
	v_mfma_i32_16x16x64_i8 v[106:109], v[182:185], v[206:209], v[106:109]
	v_mfma_i32_16x16x64_i8 v[98:101], v[190:193], v[206:209], v[98:101]
	v_mfma_i32_16x16x64_i8 v[90:93], v[182:185], v[214:217], v[90:93]
	v_mfma_i32_16x16x64_i8 v[82:85], v[190:193], v[214:217], v[82:85]
	v_mfma_i32_16x16x64_i8 v[74:77], v[182:185], v[226:229], v[74:77]
	v_mfma_i32_16x16x64_i8 v[66:69], v[190:193], v[226:229], v[66:69]
	v_mfma_i32_16x16x64_i8 v[122:125], v[186:189], v[202:205], v[122:125]
	v_mfma_i32_16x16x64_i8 v[114:117], v[194:197], v[202:205], v[114:117]
	v_mfma_i32_16x16x64_i8 v[106:109], v[186:189], v[210:213], v[106:109]
	v_mfma_i32_16x16x64_i8 v[98:101], v[194:197], v[210:213], v[98:101]
	v_mfma_i32_16x16x64_i8 v[90:93], v[186:189], v[222:225], v[90:93]
	v_mfma_i32_16x16x64_i8 v[82:85], v[194:197], v[222:225], v[82:85]
	v_mfma_i32_16x16x64_i8 v[74:77], v[186:189], v[230:233], v[74:77]
	v_mfma_i32_16x16x64_i8 v[66:69], v[194:197], v[230:233], v[66:69]
	s_barrier
	s_add_i32 s36, s38, s23
	v_lshl_add_u64 v[156:157], v[156:157], 0, s[44:45]
	s_mov_b32 m0, s36
	ds_read_b128 v[198:201], v177 offset:49152
	ds_read_b128 v[202:205], v177 offset:50176
	ds_read_b128 v[206:209], v177 offset:51200
	ds_read_b128 v[210:213], v177 offset:52224
	ds_read_b128 v[214:217], v177 offset:53248
	ds_read_b128 v[222:225], v177 offset:54272
	ds_read_b128 v[226:229], v177 offset:55296
	ds_read_b128 v[230:233], v177 offset:56320
	global_load_lds_dwordx4 v[156:157], off
	s_add_i32 m0, s36, 0x2000
	s_add_u32 s26, s26, 0x80080
	v_lshl_add_u64 v[156:157], v[174:175], 0, s[44:45]
	s_addc_u32 s27, s27, 0
	s_add_i32 s36, s39, s23
	global_load_lds_dwordx4 v[156:157], off
	v_lshl_add_u64 v[156:157], s[26:27], 0, v[162:163]
	s_mov_b32 m0, s36
	s_nop 0
	global_load_lds_dwordx4 v[156:157], off
	v_lshl_add_u64 v[156:157], s[26:27], 0, v[134:135]
	s_add_i32 m0, s36, 0x2000
	s_nop 0
	global_load_lds_dwordx4 v[156:157], off
	v_lshl_add_u64 v[156:157], v[234:235], 0, s[44:45]
	s_mov_b32 m0, s72
	s_nop 0
	global_load_lds_dwordx4 v[156:157], off
	v_lshl_add_u64 v[156:157], v[236:237], 0, s[44:45]
	s_mov_b32 m0, s73
	s_nop 0
	global_load_lds_dwordx4 v[156:157], off
	s_waitcnt vmcnt(8)
	s_waitcnt lgkmcnt(0)
	s_barrier
	v_mfma_i32_16x16x64_i8 v[62:65], v[144:147], v[198:201], v[62:65]
	v_mfma_i32_16x16x64_i8 v[54:57], v[152:155], v[198:201], v[54:57]
	s_add_i32 s21, s21, 2
	v_mfma_i32_16x16x64_i8 v[46:49], v[144:147], v[206:209], v[46:49]
	s_add_u32 s13, s13, 0x100
	v_mfma_i32_16x16x64_i8 v[38:41], v[152:155], v[206:209], v[38:41]
	s_addc_u32 s15, s15, 0
	v_mfma_i32_16x16x64_i8 v[30:33], v[144:147], v[214:217], v[30:33]
	s_add_u32 s24, s24, 0x100
	v_mfma_i32_16x16x64_i8 v[22:25], v[152:155], v[214:217], v[22:25]
	s_addc_u32 s25, s25, 0
	v_mfma_i32_16x16x64_i8 v[14:17], v[144:147], v[226:229], v[14:17]
	s_cmp_gt_u32 s21, 13
	v_mfma_i32_16x16x64_i8 v[6:9], v[152:155], v[226:229], v[6:9]
	v_mfma_i32_16x16x64_i8 v[62:65], v[148:151], v[202:205], v[62:65]
	v_mfma_i32_16x16x64_i8 v[54:57], v[178:181], v[202:205], v[54:57]
	v_mfma_i32_16x16x64_i8 v[46:49], v[148:151], v[210:213], v[46:49]
	v_mfma_i32_16x16x64_i8 v[38:41], v[178:181], v[210:213], v[38:41]
	v_mfma_i32_16x16x64_i8 v[30:33], v[148:151], v[222:225], v[30:33]
	v_mfma_i32_16x16x64_i8 v[22:25], v[178:181], v[222:225], v[22:25]
	v_mfma_i32_16x16x64_i8 v[14:17], v[148:151], v[230:233], v[14:17]
	v_mfma_i32_16x16x64_i8 v[6:9], v[178:181], v[230:233], v[6:9]
	v_mfma_i32_16x16x64_i8 v[58:61], v[182:185], v[198:201], v[58:61]
	v_mfma_i32_16x16x64_i8 v[50:53], v[190:193], v[198:201], v[50:53]
	v_mfma_i32_16x16x64_i8 v[42:45], v[182:185], v[206:209], v[42:45]
	v_mfma_i32_16x16x64_i8 v[34:37], v[190:193], v[206:209], v[34:37]
	v_mfma_i32_16x16x64_i8 v[26:29], v[182:185], v[214:217], v[26:29]
	v_mfma_i32_16x16x64_i8 v[18:21], v[190:193], v[214:217], v[18:21]
	v_mfma_i32_16x16x64_i8 v[10:13], v[182:185], v[226:229], v[10:13]
	v_mfma_i32_16x16x64_i8 v[2:5], v[190:193], v[226:229], v[2:5]
	v_mfma_i32_16x16x64_i8 v[58:61], v[186:189], v[202:205], v[58:61]
	v_mfma_i32_16x16x64_i8 v[50:53], v[194:197], v[202:205], v[50:53]
	v_mfma_i32_16x16x64_i8 v[42:45], v[186:189], v[210:213], v[42:45]
	v_mfma_i32_16x16x64_i8 v[34:37], v[194:197], v[210:213], v[34:37]
	v_mfma_i32_16x16x64_i8 v[26:29], v[186:189], v[222:225], v[26:29]
	v_mfma_i32_16x16x64_i8 v[18:21], v[194:197], v[222:225], v[18:21]
	v_mfma_i32_16x16x64_i8 v[10:13], v[186:189], v[230:233], v[10:13]
	v_mfma_i32_16x16x64_i8 v[2:5], v[194:197], v[230:233], v[2:5]
	s_barrier
	s_cbranch_scc0 .LBB0_323
	s_and_b64 vcc, exec, s[10:11]
	s_cbranch_vccz .LBB0_326
	s_barrier

.LBB0_437:
	s_add_u32 s26, s24, 0x4000
	s_addc_u32 s27, s25, 0
	s_cmpk_eq_i32 s82, 0x54
	s_cselect_b32 s58, s20, s26
	s_cselect_b32 s59, s21, s27
	s_cselect_b32 s56, s22, s80
	s_cselect_b32 s57, s23, s81
	s_add_u32 s26, s58, 0x8000
	s_addc_u32 s27, s59, 0
	s_add_i32 s36, 0, 0x10000
	s_add_i32 s38, 0, 0x14000
	v_add_u32_e32 v126, s36, v197
	v_add_u32_e32 v168, s38, v197
	ds_read_b128 v[114:117], v126
	ds_read_b128 v[118:121], v126 offset:1024
	ds_read_b128 v[122:125], v126 offset:2048
	ds_read_b128 v[126:129], v126 offset:3072
	ds_read_b128 v[138:141], v168
	ds_read_b128 v[142:145], v168 offset:1024
	ds_read_b128 v[154:157], v168 offset:2048
	ds_read_b128 v[178:181], v168 offset:3072
	v_lshl_add_u64 v[194:195], s[24:25], 0, v[176:177]
	s_add_i32 m0, s63, 0xc000
	ds_read_b128 v[182:185], v199
	ds_read_b128 v[186:189], v199 offset:1024
	ds_read_b128 v[190:193], v199 offset:2048
	ds_read_b128 v[200:203], v199 offset:3072
	ds_read_b128 v[204:207], v199 offset:4096
	ds_read_b128 v[208:211], v199 offset:5120
	ds_read_b128 v[212:215], v199 offset:6144
	ds_read_b128 v[222:225], v199 offset:7168
	global_load_lds_dwordx4 v[194:195], off
	v_lshl_add_u64 v[194:195], s[24:25], 0, v[174:175]
	s_add_i32 m0, s63, 0xe000
	s_nop 0
	global_load_lds_dwordx4 v[194:195], off
	s_waitcnt vmcnt(8)
	s_waitcnt lgkmcnt(0)
	s_barrier
	v_mfma_f32_16x16x32_bf16 v[150:153], v[114:117], v[182:185], v[150:153]
	v_mfma_f32_16x16x32_bf16 v[146:149], v[122:125], v[182:185], v[146:149]
	v_mfma_f32_16x16x32_bf16 v[110:113], v[114:117], v[190:193], v[110:113]
	v_mfma_f32_16x16x32_bf16 v[106:109], v[122:125], v[190:193], v[106:109]
	v_mfma_f32_16x16x32_bf16 v[94:97], v[114:117], v[204:207], v[94:97]
	v_mfma_f32_16x16x32_bf16 v[90:93], v[122:125], v[204:207], v[90:93]
	v_mfma_f32_16x16x32_bf16 v[78:81], v[114:117], v[212:215], v[78:81]
	v_mfma_f32_16x16x32_bf16 v[74:77], v[122:125], v[212:215], v[74:77]
	v_mfma_f32_16x16x32_bf16 v[150:153], v[118:121], v[186:189], v[150:153]
	v_mfma_f32_16x16x32_bf16 v[146:149], v[126:129], v[186:189], v[146:149]
	v_mfma_f32_16x16x32_bf16 v[110:113], v[118:121], v[200:203], v[110:113]
	v_mfma_f32_16x16x32_bf16 v[106:109], v[126:129], v[200:203], v[106:109]
	v_mfma_f32_16x16x32_bf16 v[94:97], v[118:121], v[208:211], v[94:97]
	v_mfma_f32_16x16x32_bf16 v[90:93], v[126:129], v[208:211], v[90:93]
	v_mfma_f32_16x16x32_bf16 v[78:81], v[118:121], v[222:225], v[78:81]
	v_mfma_f32_16x16x32_bf16 v[74:77], v[126:129], v[222:225], v[74:77]
	v_mfma_f32_16x16x32_bf16 v[134:137], v[138:141], v[182:185], v[134:137]
	v_mfma_f32_16x16x32_bf16 v[130:133], v[154:157], v[182:185], v[130:133]
	v_mfma_f32_16x16x32_bf16 v[102:105], v[138:141], v[190:193], v[102:105]
	v_mfma_f32_16x16x32_bf16 v[98:101], v[154:157], v[190:193], v[98:101]
	v_mfma_f32_16x16x32_bf16 v[86:89], v[138:141], v[204:207], v[86:89]
	v_mfma_f32_16x16x32_bf16 v[82:85], v[154:157], v[204:207], v[82:85]
	v_mfma_f32_16x16x32_bf16 v[70:73], v[138:141], v[212:215], v[70:73]
	v_mfma_f32_16x16x32_bf16 v[66:69], v[154:157], v[212:215], v[66:69]
	v_mfma_f32_16x16x32_bf16 v[134:137], v[142:145], v[186:189], v[134:137]
	v_mfma_f32_16x16x32_bf16 v[130:133], v[178:181], v[186:189], v[130:133]
	v_mfma_f32_16x16x32_bf16 v[102:105], v[142:145], v[200:203], v[102:105]
	v_mfma_f32_16x16x32_bf16 v[98:101], v[178:181], v[200:203], v[98:101]
	v_mfma_f32_16x16x32_bf16 v[86:89], v[142:145], v[208:211], v[86:89]
	v_mfma_f32_16x16x32_bf16 v[82:85], v[178:181], v[208:211], v[82:85]
	v_mfma_f32_16x16x32_bf16 v[70:73], v[142:145], v[222:225], v[70:73]
	v_mfma_f32_16x16x32_bf16 v[66:69], v[178:181], v[222:225], v[66:69]
	s_barrier
	s_add_i32 s36, s36, s62
	v_lshl_add_u64 v[194:195], s[56:57], 0, v[162:163]
	s_mov_b32 m0, s36
	ds_read_b128 v[182:185], v199 offset:16384
	ds_read_b128 v[186:189], v199 offset:17408
	ds_read_b128 v[190:193], v199 offset:18432
	ds_read_b128 v[200:203], v199 offset:19456
	ds_read_b128 v[204:207], v199 offset:20480
	ds_read_b128 v[208:211], v199 offset:21504
	ds_read_b128 v[212:215], v199 offset:22528
	ds_read_b128 v[222:225], v199 offset:23552
	global_load_lds_dwordx4 v[194:195], off
	s_add_i32 m0, s36, 0x2000
	s_add_u32 s36, s56, 0x160000
	v_lshl_add_u64 v[216:217], s[56:57], 0, v[172:173]
	s_addc_u32 s37, s57, 0
	s_add_i32 s38, s38, s62
	global_load_lds_dwordx4 v[216:217], off
	v_lshl_add_u64 v[226:227], s[36:37], 0, v[162:163]
	s_mov_b32 m0, s38
	s_nop 0
	global_load_lds_dwordx4 v[226:227], off
	v_lshl_add_u64 v[226:227], s[36:37], 0, v[172:173]
	s_add_i32 m0, s38, 0x2000
	s_nop 0
	global_load_lds_dwordx4 v[226:227], off
	v_lshl_add_u64 v[226:227], s[58:59], 0, v[158:159]
	s_mov_b32 m0, s63
	s_nop 0
	global_load_lds_dwordx4 v[226:227], off
	v_lshl_add_u64 v[226:227], s[58:59], 0, v[160:161]
	s_mov_b32 m0, s64
	s_nop 0
	global_load_lds_dwordx4 v[226:227], off
	s_waitcnt vmcnt(8)
	s_waitcnt lgkmcnt(0)
	s_barrier
	v_mfma_f32_16x16x32_bf16 v[62:65], v[114:117], v[182:185], v[62:65]
	v_mfma_f32_16x16x32_bf16 v[58:61], v[122:125], v[182:185], v[58:61]
	v_mfma_f32_16x16x32_bf16 v[46:49], v[114:117], v[190:193], v[46:49]
	v_mfma_f32_16x16x32_bf16 v[42:45], v[122:125], v[190:193], v[42:45]
	v_mfma_f32_16x16x32_bf16 v[30:33], v[114:117], v[204:207], v[30:33]
	v_mfma_f32_16x16x32_bf16 v[26:29], v[122:125], v[204:207], v[26:29]
	v_mfma_f32_16x16x32_bf16 v[14:17], v[114:117], v[212:215], v[14:17]
	v_mfma_f32_16x16x32_bf16 v[10:13], v[122:125], v[212:215], v[10:13]
	v_mfma_f32_16x16x32_bf16 v[62:65], v[118:121], v[186:189], v[62:65]
	v_mfma_f32_16x16x32_bf16 v[58:61], v[126:129], v[186:189], v[58:61]
	v_mfma_f32_16x16x32_bf16 v[46:49], v[118:121], v[200:203], v[46:49]
	v_mfma_f32_16x16x32_bf16 v[42:45], v[126:129], v[200:203], v[42:45]
	v_mfma_f32_16x16x32_bf16 v[30:33], v[118:121], v[208:211], v[30:33]
	v_mfma_f32_16x16x32_bf16 v[26:29], v[126:129], v[208:211], v[26:29]
	v_mfma_f32_16x16x32_bf16 v[14:17], v[118:121], v[222:225], v[14:17]
	v_mfma_f32_16x16x32_bf16 v[10:13], v[126:129], v[222:225], v[10:13]
	v_mfma_f32_16x16x32_bf16 v[54:57], v[138:141], v[182:185], v[54:57]
	v_mfma_f32_16x16x32_bf16 v[50:53], v[154:157], v[182:185], v[50:53]
	v_mfma_f32_16x16x32_bf16 v[38:41], v[138:141], v[190:193], v[38:41]
	v_mfma_f32_16x16x32_bf16 v[34:37], v[154:157], v[190:193], v[34:37]
	v_mfma_f32_16x16x32_bf16 v[22:25], v[138:141], v[204:207], v[22:25]
	v_mfma_f32_16x16x32_bf16 v[18:21], v[154:157], v[204:207], v[18:21]
	v_mfma_f32_16x16x32_bf16 v[6:9], v[138:141], v[212:215], v[6:9]
	v_mfma_f32_16x16x32_bf16 v[2:5], v[154:157], v[212:215], v[2:5]
	v_mfma_f32_16x16x32_bf16 v[54:57], v[142:145], v[186:189], v[54:57]
	v_mfma_f32_16x16x32_bf16 v[50:53], v[178:181], v[186:189], v[50:53]
	v_mfma_f32_16x16x32_bf16 v[38:41], v[142:145], v[200:203], v[38:41]
	v_mfma_f32_16x16x32_bf16 v[34:37], v[178:181], v[200:203], v[34:37]
	v_mfma_f32_16x16x32_bf16 v[22:25], v[142:145], v[208:211], v[22:25]
	v_mfma_f32_16x16x32_bf16 v[18:21], v[178:181], v[208:211], v[18:21]
	v_mfma_f32_16x16x32_bf16 v[6:9], v[142:145], v[222:225], v[6:9]
	v_mfma_f32_16x16x32_bf16 v[2:5], v[178:181], v[222:225], v[2:5]
	s_barrier
	s_add_i32 s38, 0, 0x18000
	s_add_i32 s39, 0, 0x1c000
	v_add_u32_e32 v126, s38, v197
	v_add_u32_e32 v168, s39, v197
	ds_read_b128 v[114:117], v126
	ds_read_b128 v[118:121], v126 offset:1024
	ds_read_b128 v[122:125], v126 offset:2048
	ds_read_b128 v[126:129], v126 offset:3072
	ds_read_b128 v[138:141], v168
	ds_read_b128 v[142:145], v168 offset:1024
	ds_read_b128 v[154:157], v168 offset:2048
	ds_read_b128 v[178:181], v168 offset:3072
	s_add_u32 s36, s58, 0x4000
	s_addc_u32 s37, s59, 0
	s_mov_b32 m0, s65
	v_lshl_add_u64 v[226:227], s[36:37], 0, v[158:159]
	ds_read_b128 v[182:185], v199 offset:32768
	ds_read_b128 v[186:189], v199 offset:33792
	ds_read_b128 v[190:193], v199 offset:34816
	ds_read_b128 v[200:203], v199 offset:35840
	ds_read_b128 v[204:207], v199 offset:36864
	ds_read_b128 v[208:211], v199 offset:37888
	ds_read_b128 v[212:215], v199 offset:38912
	ds_read_b128 v[222:225], v199 offset:39936
	global_load_lds_dwordx4 v[226:227], off
	v_lshl_add_u64 v[226:227], s[36:37], 0, v[160:161]
	s_mov_b32 m0, s66
	s_nop 0
	global_load_lds_dwordx4 v[226:227], off
	s_waitcnt vmcnt(8)
	s_waitcnt lgkmcnt(0)
	s_barrier
	v_mfma_f32_16x16x32_bf16 v[150:153], v[114:117], v[182:185], v[150:153]
	v_mfma_f32_16x16x32_bf16 v[146:149], v[122:125], v[182:185], v[146:149]
	v_mfma_f32_16x16x32_bf16 v[110:113], v[114:117], v[190:193], v[110:113]
	v_mfma_f32_16x16x32_bf16 v[106:109], v[122:125], v[190:193], v[106:109]
	v_mfma_f32_16x16x32_bf16 v[94:97], v[114:117], v[204:207], v[94:97]
	v_mfma_f32_16x16x32_bf16 v[90:93], v[122:125], v[204:207], v[90:93]
	v_mfma_f32_16x16x32_bf16 v[78:81], v[114:117], v[212:215], v[78:81]
	v_mfma_f32_16x16x32_bf16 v[74:77], v[122:125], v[212:215], v[74:77]
	v_mfma_f32_16x16x32_bf16 v[150:153], v[118:121], v[186:189], v[150:153]
	v_mfma_f32_16x16x32_bf16 v[146:149], v[126:129], v[186:189], v[146:149]
	v_mfma_f32_16x16x32_bf16 v[110:113], v[118:121], v[200:203], v[110:113]
	v_mfma_f32_16x16x32_bf16 v[106:109], v[126:129], v[200:203], v[106:109]
	v_mfma_f32_16x16x32_bf16 v[94:97], v[118:121], v[208:211], v[94:97]
	v_mfma_f32_16x16x32_bf16 v[90:93], v[126:129], v[208:211], v[90:93]
	v_mfma_f32_16x16x32_bf16 v[78:81], v[118:121], v[222:225], v[78:81]
	v_mfma_f32_16x16x32_bf16 v[74:77], v[126:129], v[222:225], v[74:77]
	v_mfma_f32_16x16x32_bf16 v[134:137], v[138:141], v[182:185], v[134:137]
	v_mfma_f32_16x16x32_bf16 v[130:133], v[154:157], v[182:185], v[130:133]
	v_mfma_f32_16x16x32_bf16 v[102:105], v[138:141], v[190:193], v[102:105]
	v_mfma_f32_16x16x32_bf16 v[98:101], v[154:157], v[190:193], v[98:101]
	v_mfma_f32_16x16x32_bf16 v[86:89], v[138:141], v[204:207], v[86:89]
	v_mfma_f32_16x16x32_bf16 v[82:85], v[154:157], v[204:207], v[82:85]
	v_mfma_f32_16x16x32_bf16 v[70:73], v[138:141], v[212:215], v[70:73]
	v_mfma_f32_16x16x32_bf16 v[66:69], v[154:157], v[212:215], v[66:69]
	v_mfma_f32_16x16x32_bf16 v[134:137], v[142:145], v[186:189], v[134:137]
	v_mfma_f32_16x16x32_bf16 v[130:133], v[178:181], v[186:189], v[130:133]
	v_mfma_f32_16x16x32_bf16 v[102:105], v[142:145], v[200:203], v[102:105]
	v_mfma_f32_16x16x32_bf16 v[98:101], v[178:181], v[200:203], v[98:101]
	v_mfma_f32_16x16x32_bf16 v[86:89], v[142:145], v[208:211], v[86:89]
	v_mfma_f32_16x16x32_bf16 v[82:85], v[178:181], v[208:211], v[82:85]
	v_mfma_f32_16x16x32_bf16 v[70:73], v[142:145], v[222:225], v[70:73]
	v_mfma_f32_16x16x32_bf16 v[66:69], v[178:181], v[222:225], v[66:69]
	s_barrier
	s_add_i32 s36, s38, s62
	v_lshl_add_u64 v[194:195], v[194:195], 0, s[44:45]
	s_mov_b32 m0, s36
	ds_read_b128 v[182:185], v199 offset:49152
	ds_read_b128 v[186:189], v199 offset:50176
	ds_read_b128 v[190:193], v199 offset:51200
	ds_read_b128 v[200:203], v199 offset:52224
	ds_read_b128 v[204:207], v199 offset:53248
	ds_read_b128 v[208:211], v199 offset:54272
	ds_read_b128 v[212:215], v199 offset:55296
	ds_read_b128 v[222:225], v199 offset:56320
	global_load_lds_dwordx4 v[194:195], off
	s_add_i32 m0, s36, 0x2000
	s_add_u32 s36, s56, 0x160080
	v_lshl_add_u64 v[194:195], v[216:217], 0, s[44:45]
	s_addc_u32 s37, s57, 0
	s_add_i32 s38, s39, s62
	global_load_lds_dwordx4 v[194:195], off
	v_lshl_add_u64 v[194:195], s[36:37], 0, v[162:163]
	s_mov_b32 m0, s38
	s_nop 0
	global_load_lds_dwordx4 v[194:195], off
	v_lshl_add_u64 v[194:195], s[36:37], 0, v[172:173]
	s_add_i32 m0, s38, 0x2000
	s_nop 0
	global_load_lds_dwordx4 v[194:195], off
	v_lshl_add_u64 v[194:195], s[26:27], 0, v[158:159]
	s_mov_b32 m0, s67
	s_nop 0
	global_load_lds_dwordx4 v[194:195], off
	v_lshl_add_u64 v[194:195], s[26:27], 0, v[160:161]
	s_mov_b32 m0, s68
	s_nop 0
	global_load_lds_dwordx4 v[194:195], off
	s_waitcnt vmcnt(8)
	s_waitcnt lgkmcnt(0)
	s_barrier
	v_mfma_f32_16x16x32_bf16 v[62:65], v[114:117], v[182:185], v[62:65]
	v_mfma_f32_16x16x32_bf16 v[58:61], v[122:125], v[182:185], v[58:61]
	s_add_i32 s82, s82, 2
	v_mfma_f32_16x16x32_bf16 v[46:49], v[114:117], v[190:193], v[46:49]
	s_add_u32 s24, s24, 0x10000
	v_mfma_f32_16x16x32_bf16 v[42:45], v[122:125], v[190:193], v[42:45]
	s_addc_u32 s25, s25, 0
	v_mfma_f32_16x16x32_bf16 v[30:33], v[114:117], v[204:207], v[30:33]
	s_add_u32 s80, s80, 0x100
	v_mfma_f32_16x16x32_bf16 v[26:29], v[122:125], v[204:207], v[26:29]
	s_addc_u32 s81, s81, 0
	v_mfma_f32_16x16x32_bf16 v[14:17], v[114:117], v[212:215], v[14:17]
	s_cmpk_gt_u32 s82, 0x55
	v_mfma_f32_16x16x32_bf16 v[10:13], v[122:125], v[212:215], v[10:13]
	v_mfma_f32_16x16x32_bf16 v[62:65], v[118:121], v[186:189], v[62:65]
	v_mfma_f32_16x16x32_bf16 v[58:61], v[126:129], v[186:189], v[58:61]
	v_mfma_f32_16x16x32_bf16 v[46:49], v[118:121], v[200:203], v[46:49]
	v_mfma_f32_16x16x32_bf16 v[42:45], v[126:129], v[200:203], v[42:45]
	v_mfma_f32_16x16x32_bf16 v[30:33], v[118:121], v[208:211], v[30:33]
	v_mfma_f32_16x16x32_bf16 v[26:29], v[126:129], v[208:211], v[26:29]
	v_mfma_f32_16x16x32_bf16 v[14:17], v[118:121], v[222:225], v[14:17]
	v_mfma_f32_16x16x32_bf16 v[10:13], v[126:129], v[222:225], v[10:13]
	v_mfma_f32_16x16x32_bf16 v[54:57], v[138:141], v[182:185], v[54:57]
	v_mfma_f32_16x16x32_bf16 v[50:53], v[154:157], v[182:185], v[50:53]
	v_mfma_f32_16x16x32_bf16 v[38:41], v[138:141], v[190:193], v[38:41]
	v_mfma_f32_16x16x32_bf16 v[34:37], v[154:157], v[190:193], v[34:37]
	v_mfma_f32_16x16x32_bf16 v[22:25], v[138:141], v[204:207], v[22:25]
	v_mfma_f32_16x16x32_bf16 v[18:21], v[154:157], v[204:207], v[18:21]
	v_mfma_f32_16x16x32_bf16 v[6:9], v[138:141], v[212:215], v[6:9]
	v_mfma_f32_16x16x32_bf16 v[2:5], v[154:157], v[212:215], v[2:5]
	v_mfma_f32_16x16x32_bf16 v[54:57], v[142:145], v[186:189], v[54:57]
	v_mfma_f32_16x16x32_bf16 v[50:53], v[178:181], v[186:189], v[50:53]
	v_mfma_f32_16x16x32_bf16 v[38:41], v[142:145], v[200:203], v[38:41]
	v_mfma_f32_16x16x32_bf16 v[34:37], v[178:181], v[200:203], v[34:37]
	v_mfma_f32_16x16x32_bf16 v[22:25], v[142:145], v[208:211], v[22:25]
	v_mfma_f32_16x16x32_bf16 v[18:21], v[178:181], v[208:211], v[18:21]
	v_mfma_f32_16x16x32_bf16 v[6:9], v[142:145], v[222:225], v[6:9]
	v_mfma_f32_16x16x32_bf16 v[2:5], v[178:181], v[222:225], v[2:5]
	s_barrier
	s_cbranch_scc0 .LBB0_437
	s_and_b64 vcc, exec, s[18:19]
	s_cbranch_vccz .LBB0_440
	s_barrier

.LBB0_643:
	s_add_u32 s36, s58, 0xfff80080
	s_addc_u32 s37, s59, -1
	s_add_i32 s38, 0, 0x10000
	s_cmp_eq_u32 s64, 28
	s_cselect_b32 s63, s23, s37
	s_cselect_b32 s62, s22, s36
	s_cselect_b32 s61, s25, s57
	s_cselect_b32 s60, s24, s21
	s_add_i32 s39, 0, 0x14000
	v_add_u32_e32 v152, s38, v161
	v_add_u32_e32 v156, s39, v161
	ds_read_b128 v[140:143], v152
	ds_read_b128 v[144:147], v152 offset:1024
	ds_read_b128 v[148:151], v152 offset:2048
	ds_read_b128 v[152:155], v152 offset:3072
	ds_read_b128 v[180:183], v156
	ds_read_b128 v[184:187], v156 offset:1024
	ds_read_b128 v[188:191], v156 offset:2048
	ds_read_b128 v[192:195], v156 offset:3072
	v_lshl_add_u64 v[172:173], s[58:59], 0, v[138:139]
	s_add_i32 m0, s41, 0xc000
	ds_read_b128 v[196:199], v179
	ds_read_b128 v[200:203], v179 offset:1024
	ds_read_b128 v[204:207], v179 offset:2048
	ds_read_b128 v[208:211], v179 offset:3072
	ds_read_b128 v[212:215], v179 offset:4096
	ds_read_b128 v[222:225], v179 offset:5120
	ds_read_b128 v[226:229], v179 offset:6144
	ds_read_b128 v[230:233], v179 offset:7168
	global_load_lds_dwordx4 v[172:173], off
	v_lshl_add_u64 v[172:173], s[58:59], 0, v[136:137]
	s_add_i32 m0, s41, 0xe000
	s_nop 0
	global_load_lds_dwordx4 v[172:173], off
	s_waitcnt vmcnt(8)
	s_waitcnt lgkmcnt(0)
	s_barrier
	v_mfma_f32_16x16x32_bf16 v[126:129], v[140:143], v[196:199], v[126:129]
	v_mfma_f32_16x16x32_bf16 v[86:89], v[148:151], v[196:199], v[86:89]
	v_mfma_f32_16x16x32_bf16 v[118:121], v[140:143], v[204:207], v[118:121]
	v_mfma_f32_16x16x32_bf16 v[94:97], v[148:151], v[204:207], v[94:97]
	v_mfma_f32_16x16x32_bf16 v[106:109], v[140:143], v[212:215], v[106:109]
	v_mfma_f32_16x16x32_bf16 v[102:105], v[148:151], v[212:215], v[102:105]
	v_mfma_f32_16x16x32_bf16 v[78:81], v[140:143], v[226:229], v[78:81]
	v_mfma_f32_16x16x32_bf16 v[74:77], v[148:151], v[226:229], v[74:77]
	v_mfma_f32_16x16x32_bf16 v[126:129], v[144:147], v[200:203], v[126:129]
	v_mfma_f32_16x16x32_bf16 v[86:89], v[152:155], v[200:203], v[86:89]
	v_mfma_f32_16x16x32_bf16 v[118:121], v[144:147], v[208:211], v[118:121]
	v_mfma_f32_16x16x32_bf16 v[94:97], v[152:155], v[208:211], v[94:97]
	v_mfma_f32_16x16x32_bf16 v[106:109], v[144:147], v[222:225], v[106:109]
	v_mfma_f32_16x16x32_bf16 v[102:105], v[152:155], v[222:225], v[102:105]
	v_mfma_f32_16x16x32_bf16 v[78:81], v[144:147], v[230:233], v[78:81]
	v_mfma_f32_16x16x32_bf16 v[74:77], v[152:155], v[230:233], v[74:77]
	v_mfma_f32_16x16x32_bf16 v[122:125], v[180:183], v[196:199], v[122:125]
	v_mfma_f32_16x16x32_bf16 v[98:101], v[188:191], v[196:199], v[98:101]
	v_mfma_f32_16x16x32_bf16 v[114:117], v[180:183], v[204:207], v[114:117]
	v_mfma_f32_16x16x32_bf16 v[110:113], v[188:191], v[204:207], v[110:113]
	v_mfma_f32_16x16x32_bf16 v[90:93], v[180:183], v[212:215], v[90:93]
	v_mfma_f32_16x16x32_bf16 v[82:85], v[188:191], v[212:215], v[82:85]
	v_mfma_f32_16x16x32_bf16 v[70:73], v[180:183], v[226:229], v[70:73]
	v_mfma_f32_16x16x32_bf16 v[66:69], v[188:191], v[226:229], v[66:69]
	v_mfma_f32_16x16x32_bf16 v[122:125], v[184:187], v[200:203], v[122:125]
	v_mfma_f32_16x16x32_bf16 v[98:101], v[192:195], v[200:203], v[98:101]
	v_mfma_f32_16x16x32_bf16 v[114:117], v[184:187], v[208:211], v[114:117]
	v_mfma_f32_16x16x32_bf16 v[110:113], v[192:195], v[208:211], v[110:113]
	v_mfma_f32_16x16x32_bf16 v[90:93], v[184:187], v[222:225], v[90:93]
	v_mfma_f32_16x16x32_bf16 v[82:85], v[192:195], v[222:225], v[82:85]
	v_mfma_f32_16x16x32_bf16 v[70:73], v[184:187], v[230:233], v[70:73]
	v_mfma_f32_16x16x32_bf16 v[66:69], v[192:195], v[230:233], v[66:69]
	s_barrier
	s_add_i32 s36, s38, s72
	v_lshl_add_u64 v[172:173], s[60:61], 0, v[162:163]
	s_mov_b32 m0, s36
	ds_read_b128 v[196:199], v179 offset:16384
	ds_read_b128 v[200:203], v179 offset:17408
	ds_read_b128 v[204:207], v179 offset:18432
	ds_read_b128 v[208:211], v179 offset:19456
	ds_read_b128 v[212:215], v179 offset:20480
	ds_read_b128 v[222:225], v179 offset:21504
	ds_read_b128 v[226:229], v179 offset:22528
	ds_read_b128 v[230:233], v179 offset:23552
	global_load_lds_dwordx4 v[172:173], off
	s_add_i32 m0, s36, 0x2000
	s_add_u32 s36, s60, 0x80000
	v_lshl_add_u64 v[216:217], s[60:61], 0, v[134:135]
	s_addc_u32 s37, s61, 0
	s_add_i32 s38, s39, s72
	global_load_lds_dwordx4 v[216:217], off
	v_lshl_add_u64 v[234:235], s[36:37], 0, v[162:163]
	s_mov_b32 m0, s38
	v_lshl_add_u64 v[236:237], s[62:63], 0, v[132:133]
	global_load_lds_dwordx4 v[234:235], off
	v_lshl_add_u64 v[234:235], s[36:37], 0, v[134:135]
	s_add_i32 m0, s38, 0x2000
	s_nop 0
	global_load_lds_dwordx4 v[234:235], off
	v_lshl_add_u64 v[234:235], s[62:63], 0, v[130:131]
	s_mov_b32 m0, s41
	s_nop 0
	global_load_lds_dwordx4 v[234:235], off
	s_mov_b32 m0, s66
	s_nop 0
	global_load_lds_dwordx4 v[236:237], off
	s_waitcnt vmcnt(8)
	s_waitcnt lgkmcnt(0)
	s_barrier
	v_mfma_f32_16x16x32_bf16 v[62:65], v[140:143], v[196:199], v[62:65]
	v_mfma_f32_16x16x32_bf16 v[58:61], v[148:151], v[196:199], v[58:61]
	v_mfma_f32_16x16x32_bf16 v[46:49], v[140:143], v[204:207], v[46:49]
	v_mfma_f32_16x16x32_bf16 v[42:45], v[148:151], v[204:207], v[42:45]
	v_mfma_f32_16x16x32_bf16 v[30:33], v[140:143], v[212:215], v[30:33]
	v_mfma_f32_16x16x32_bf16 v[26:29], v[148:151], v[212:215], v[26:29]
	v_mfma_f32_16x16x32_bf16 v[14:17], v[140:143], v[226:229], v[14:17]
	v_mfma_f32_16x16x32_bf16 v[10:13], v[148:151], v[226:229], v[10:13]
	v_mfma_f32_16x16x32_bf16 v[62:65], v[144:147], v[200:203], v[62:65]
	v_mfma_f32_16x16x32_bf16 v[58:61], v[152:155], v[200:203], v[58:61]
	v_mfma_f32_16x16x32_bf16 v[46:49], v[144:147], v[208:211], v[46:49]
	v_mfma_f32_16x16x32_bf16 v[42:45], v[152:155], v[208:211], v[42:45]
	v_mfma_f32_16x16x32_bf16 v[30:33], v[144:147], v[222:225], v[30:33]
	v_mfma_f32_16x16x32_bf16 v[26:29], v[152:155], v[222:225], v[26:29]
	v_mfma_f32_16x16x32_bf16 v[14:17], v[144:147], v[230:233], v[14:17]
	v_mfma_f32_16x16x32_bf16 v[10:13], v[152:155], v[230:233], v[10:13]
	v_mfma_f32_16x16x32_bf16 v[54:57], v[180:183], v[196:199], v[54:57]
	v_mfma_f32_16x16x32_bf16 v[50:53], v[188:191], v[196:199], v[50:53]
	v_mfma_f32_16x16x32_bf16 v[38:41], v[180:183], v[204:207], v[38:41]
	v_mfma_f32_16x16x32_bf16 v[34:37], v[188:191], v[204:207], v[34:37]
	v_mfma_f32_16x16x32_bf16 v[22:25], v[180:183], v[212:215], v[22:25]
	v_mfma_f32_16x16x32_bf16 v[18:21], v[188:191], v[212:215], v[18:21]
	v_mfma_f32_16x16x32_bf16 v[6:9], v[180:183], v[226:229], v[6:9]
	v_mfma_f32_16x16x32_bf16 v[2:5], v[188:191], v[226:229], v[2:5]
	v_mfma_f32_16x16x32_bf16 v[54:57], v[184:187], v[200:203], v[54:57]
	v_mfma_f32_16x16x32_bf16 v[50:53], v[192:195], v[200:203], v[50:53]
	v_mfma_f32_16x16x32_bf16 v[38:41], v[184:187], v[208:211], v[38:41]
	v_mfma_f32_16x16x32_bf16 v[34:37], v[192:195], v[208:211], v[34:37]
	v_mfma_f32_16x16x32_bf16 v[22:25], v[184:187], v[222:225], v[22:25]
	v_mfma_f32_16x16x32_bf16 v[18:21], v[192:195], v[222:225], v[18:21]
	v_mfma_f32_16x16x32_bf16 v[6:9], v[184:187], v[230:233], v[6:9]
	v_mfma_f32_16x16x32_bf16 v[2:5], v[192:195], v[230:233], v[2:5]
	s_barrier
	s_add_i32 s38, 0, 0x18000
	s_add_i32 s39, 0, 0x1c000
	v_add_u32_e32 v152, s38, v161
	v_add_u32_e32 v156, s39, v161
	ds_read_b128 v[140:143], v152
	ds_read_b128 v[144:147], v152 offset:1024
	ds_read_b128 v[148:151], v152 offset:2048
	ds_read_b128 v[152:155], v152 offset:3072
	ds_read_b128 v[180:183], v156
	ds_read_b128 v[184:187], v156 offset:1024
	ds_read_b128 v[188:191], v156 offset:2048
	ds_read_b128 v[192:195], v156 offset:3072
	s_add_u32 s36, s62, 0x80000
	s_addc_u32 s37, s63, 0
	s_mov_b32 m0, s74
	v_lshl_add_u64 v[238:239], s[36:37], 0, v[130:131]
	ds_read_b128 v[196:199], v179 offset:32768
	ds_read_b128 v[200:203], v179 offset:33792
	ds_read_b128 v[204:207], v179 offset:34816
	ds_read_b128 v[208:211], v179 offset:35840
	ds_read_b128 v[212:215], v179 offset:36864
	ds_read_b128 v[222:225], v179 offset:37888
	ds_read_b128 v[226:229], v179 offset:38912
	ds_read_b128 v[230:233], v179 offset:39936
	global_load_lds_dwordx4 v[238:239], off
	v_lshl_add_u64 v[238:239], s[36:37], 0, v[132:133]
	s_mov_b32 m0, s75
	s_nop 0
	global_load_lds_dwordx4 v[238:239], off
	s_waitcnt vmcnt(8)
	s_waitcnt lgkmcnt(0)
	s_barrier
	v_mfma_f32_16x16x32_bf16 v[126:129], v[140:143], v[196:199], v[126:129]
	v_mfma_f32_16x16x32_bf16 v[86:89], v[148:151], v[196:199], v[86:89]
	v_mfma_f32_16x16x32_bf16 v[118:121], v[140:143], v[204:207], v[118:121]
	v_mfma_f32_16x16x32_bf16 v[94:97], v[148:151], v[204:207], v[94:97]
	v_mfma_f32_16x16x32_bf16 v[106:109], v[140:143], v[212:215], v[106:109]
	v_mfma_f32_16x16x32_bf16 v[102:105], v[148:151], v[212:215], v[102:105]
	v_mfma_f32_16x16x32_bf16 v[78:81], v[140:143], v[226:229], v[78:81]
	v_mfma_f32_16x16x32_bf16 v[74:77], v[148:151], v[226:229], v[74:77]
	v_mfma_f32_16x16x32_bf16 v[126:129], v[144:147], v[200:203], v[126:129]
	v_mfma_f32_16x16x32_bf16 v[86:89], v[152:155], v[200:203], v[86:89]
	v_mfma_f32_16x16x32_bf16 v[118:121], v[144:147], v[208:211], v[118:121]
	v_mfma_f32_16x16x32_bf16 v[94:97], v[152:155], v[208:211], v[94:97]
	v_mfma_f32_16x16x32_bf16 v[106:109], v[144:147], v[222:225], v[106:109]
	v_mfma_f32_16x16x32_bf16 v[102:105], v[152:155], v[222:225], v[102:105]
	v_mfma_f32_16x16x32_bf16 v[78:81], v[144:147], v[230:233], v[78:81]
	v_mfma_f32_16x16x32_bf16 v[74:77], v[152:155], v[230:233], v[74:77]
	v_mfma_f32_16x16x32_bf16 v[122:125], v[180:183], v[196:199], v[122:125]
	v_mfma_f32_16x16x32_bf16 v[98:101], v[188:191], v[196:199], v[98:101]
	v_mfma_f32_16x16x32_bf16 v[114:117], v[180:183], v[204:207], v[114:117]
	v_mfma_f32_16x16x32_bf16 v[110:113], v[188:191], v[204:207], v[110:113]
	v_mfma_f32_16x16x32_bf16 v[90:93], v[180:183], v[212:215], v[90:93]
	v_mfma_f32_16x16x32_bf16 v[82:85], v[188:191], v[212:215], v[82:85]
	v_mfma_f32_16x16x32_bf16 v[70:73], v[180:183], v[226:229], v[70:73]
	v_mfma_f32_16x16x32_bf16 v[66:69], v[188:191], v[226:229], v[66:69]
	v_mfma_f32_16x16x32_bf16 v[122:125], v[184:187], v[200:203], v[122:125]
	v_mfma_f32_16x16x32_bf16 v[98:101], v[192:195], v[200:203], v[98:101]
	v_mfma_f32_16x16x32_bf16 v[114:117], v[184:187], v[208:211], v[114:117]
	v_mfma_f32_16x16x32_bf16 v[110:113], v[192:195], v[208:211], v[110:113]
	v_mfma_f32_16x16x32_bf16 v[90:93], v[184:187], v[222:225], v[90:93]
	v_mfma_f32_16x16x32_bf16 v[82:85], v[192:195], v[222:225], v[82:85]
	v_mfma_f32_16x16x32_bf16 v[70:73], v[184:187], v[230:233], v[70:73]
	v_mfma_f32_16x16x32_bf16 v[66:69], v[192:195], v[230:233], v[66:69]
	s_barrier
	s_add_i32 s36, s38, s72
	v_lshl_add_u64 v[172:173], v[172:173], 0, s[44:45]
	s_mov_b32 m0, s36
	ds_read_b128 v[196:199], v179 offset:49152
	ds_read_b128 v[200:203], v179 offset:50176
	ds_read_b128 v[204:207], v179 offset:51200
	ds_read_b128 v[208:211], v179 offset:52224
	ds_read_b128 v[212:215], v179 offset:53248
	ds_read_b128 v[222:225], v179 offset:54272
	ds_read_b128 v[226:229], v179 offset:55296
	ds_read_b128 v[230:233], v179 offset:56320
	global_load_lds_dwordx4 v[172:173], off
	s_add_i32 m0, s36, 0x2000
	s_add_u32 s36, s60, 0x80080
	v_lshl_add_u64 v[172:173], v[216:217], 0, s[44:45]
	s_addc_u32 s37, s61, 0
	s_add_i32 s38, s39, s72
	global_load_lds_dwordx4 v[172:173], off
	v_lshl_add_u64 v[172:173], s[36:37], 0, v[162:163]
	s_mov_b32 m0, s38
	s_nop 0
	global_load_lds_dwordx4 v[172:173], off
	v_lshl_add_u64 v[172:173], s[36:37], 0, v[134:135]
	s_add_i32 m0, s38, 0x2000
	s_nop 0
	global_load_lds_dwordx4 v[172:173], off
	v_lshl_add_u64 v[172:173], v[234:235], 0, s[44:45]
	s_mov_b32 m0, s76
	s_nop 0
	global_load_lds_dwordx4 v[172:173], off
	v_lshl_add_u64 v[172:173], v[236:237], 0, s[44:45]
	s_mov_b32 m0, s77
	s_nop 0
	global_load_lds_dwordx4 v[172:173], off
	s_waitcnt vmcnt(8)
	s_waitcnt lgkmcnt(0)
	s_barrier
	v_mfma_f32_16x16x32_bf16 v[62:65], v[140:143], v[196:199], v[62:65]
	v_mfma_f32_16x16x32_bf16 v[58:61], v[148:151], v[196:199], v[58:61]
	s_add_i32 s64, s64, 2
	v_mfma_f32_16x16x32_bf16 v[46:49], v[140:143], v[204:207], v[46:49]
	s_add_u32 s21, s21, 0x100
	v_mfma_f32_16x16x32_bf16 v[42:45], v[148:151], v[204:207], v[42:45]
	s_addc_u32 s57, s57, 0
	v_mfma_f32_16x16x32_bf16 v[30:33], v[140:143], v[212:215], v[30:33]
	s_add_u32 s58, s58, 0x100
	v_mfma_f32_16x16x32_bf16 v[26:29], v[148:151], v[212:215], v[26:29]
	s_addc_u32 s59, s59, 0
	v_mfma_f32_16x16x32_bf16 v[14:17], v[140:143], v[226:229], v[14:17]
	s_cmp_gt_u32 s64, 29
	v_mfma_f32_16x16x32_bf16 v[10:13], v[148:151], v[226:229], v[10:13]
	v_mfma_f32_16x16x32_bf16 v[62:65], v[144:147], v[200:203], v[62:65]
	v_mfma_f32_16x16x32_bf16 v[58:61], v[152:155], v[200:203], v[58:61]
	v_mfma_f32_16x16x32_bf16 v[46:49], v[144:147], v[208:211], v[46:49]
	v_mfma_f32_16x16x32_bf16 v[42:45], v[152:155], v[208:211], v[42:45]
	v_mfma_f32_16x16x32_bf16 v[30:33], v[144:147], v[222:225], v[30:33]
	v_mfma_f32_16x16x32_bf16 v[26:29], v[152:155], v[222:225], v[26:29]
	v_mfma_f32_16x16x32_bf16 v[14:17], v[144:147], v[230:233], v[14:17]
	v_mfma_f32_16x16x32_bf16 v[10:13], v[152:155], v[230:233], v[10:13]
	v_mfma_f32_16x16x32_bf16 v[54:57], v[180:183], v[196:199], v[54:57]
	v_mfma_f32_16x16x32_bf16 v[50:53], v[188:191], v[196:199], v[50:53]
	v_mfma_f32_16x16x32_bf16 v[38:41], v[180:183], v[204:207], v[38:41]
	v_mfma_f32_16x16x32_bf16 v[34:37], v[188:191], v[204:207], v[34:37]
	v_mfma_f32_16x16x32_bf16 v[22:25], v[180:183], v[212:215], v[22:25]
	v_mfma_f32_16x16x32_bf16 v[18:21], v[188:191], v[212:215], v[18:21]
	v_mfma_f32_16x16x32_bf16 v[6:9], v[180:183], v[226:229], v[6:9]
	v_mfma_f32_16x16x32_bf16 v[2:5], v[188:191], v[226:229], v[2:5]
	v_mfma_f32_16x16x32_bf16 v[54:57], v[184:187], v[200:203], v[54:57]
	v_mfma_f32_16x16x32_bf16 v[50:53], v[192:195], v[200:203], v[50:53]
	v_mfma_f32_16x16x32_bf16 v[38:41], v[184:187], v[208:211], v[38:41]
	v_mfma_f32_16x16x32_bf16 v[34:37], v[192:195], v[208:211], v[34:37]
	v_mfma_f32_16x16x32_bf16 v[22:25], v[184:187], v[222:225], v[22:25]
	v_mfma_f32_16x16x32_bf16 v[18:21], v[192:195], v[222:225], v[18:21]
	v_mfma_f32_16x16x32_bf16 v[6:9], v[184:187], v[230:233], v[6:9]
	v_mfma_f32_16x16x32_bf16 v[2:5], v[192:195], v[230:233], v[2:5]
	s_barrier
	s_cbranch_scc0 .LBB0_643
	s_and_b64 vcc, exec, s[16:17]
	s_cbranch_vccz .LBB0_646
	s_barrier

.LBB0_696:
	s_add_u32 s36, s26, 0xfffc0080
	s_addc_u32 s37, s27, -1
	s_add_i32 s38, 0, 0x10000
	s_cmp_eq_u32 s60, 12
	s_cselect_b32 s59, s19, s37
	s_cselect_b32 s58, s18, s36
	v_add_u32_e32 v140, s38, v149
	s_cselect_b32 s57, s21, s17
	s_cselect_b32 s56, s20, s15
	s_add_i32 s39, 0, 0x14000
	ds_read_b128 v[156:159], v140
	ds_read_b128 v[172:175], v140 offset:1024
	ds_read_b128 v[190:193], v140 offset:2048
	ds_read_b128 v[194:197], v140 offset:3072
	v_add_u32_e32 v140, s39, v149
	ds_read_b128 v[198:201], v140
	ds_read_b128 v[202:205], v140 offset:1024
	ds_read_b128 v[206:209], v140 offset:2048
	ds_read_b128 v[210:213], v140 offset:3072
	v_lshl_add_u64 v[160:161], s[26:27], 0, v[138:139]
	s_add_i32 m0, s25, 0xc000
	ds_read_b128 v[214:217], v189
	ds_read_b128 v[222:225], v189 offset:1024
	ds_read_b128 v[226:229], v189 offset:2048
	ds_read_b128 v[230:233], v189 offset:3072
	ds_read_b128 v[234:237], v189 offset:4096
	ds_read_b128 v[238:241], v189 offset:5120
	ds_read_b128 v[242:245], v189 offset:6144
	ds_read_b128 v[246:249], v189 offset:7168
	global_load_lds_dwordx4 v[160:161], off
	v_lshl_add_u64 v[160:161], s[26:27], 0, v[136:137]
	s_add_i32 m0, s25, 0xe000
	s_nop 0
	global_load_lds_dwordx4 v[160:161], off
	s_waitcnt vmcnt(8)
	s_waitcnt lgkmcnt(0)
	s_barrier
	v_mfma_i32_16x16x64_i8 v[126:129], v[156:159], v[214:217], v[126:129]
	v_mfma_i32_16x16x64_i8 v[122:125], v[190:193], v[214:217], v[122:125]
	v_mfma_i32_16x16x64_i8 v[118:121], v[156:159], v[226:229], v[118:121]
	v_mfma_i32_16x16x64_i8 v[114:117], v[190:193], v[226:229], v[114:117]
	v_mfma_i32_16x16x64_i8 v[110:113], v[156:159], v[234:237], v[110:113]
	v_mfma_i32_16x16x64_i8 v[106:109], v[190:193], v[234:237], v[106:109]
	v_mfma_i32_16x16x64_i8 v[102:105], v[156:159], v[242:245], v[102:105]
	v_mfma_i32_16x16x64_i8 v[98:101], v[190:193], v[242:245], v[98:101]
	v_mfma_i32_16x16x64_i8 v[126:129], v[172:175], v[222:225], v[126:129]
	v_mfma_i32_16x16x64_i8 v[122:125], v[194:197], v[222:225], v[122:125]
	v_mfma_i32_16x16x64_i8 v[118:121], v[172:175], v[230:233], v[118:121]
	v_mfma_i32_16x16x64_i8 v[114:117], v[194:197], v[230:233], v[114:117]
	v_mfma_i32_16x16x64_i8 v[110:113], v[172:175], v[238:241], v[110:113]
	v_mfma_i32_16x16x64_i8 v[106:109], v[194:197], v[238:241], v[106:109]
	v_mfma_i32_16x16x64_i8 v[102:105], v[172:175], v[246:249], v[102:105]
	v_mfma_i32_16x16x64_i8 v[98:101], v[194:197], v[246:249], v[98:101]
	v_mfma_i32_16x16x64_i8 v[62:65], v[198:201], v[214:217], v[62:65]
	v_mfma_i32_16x16x64_i8 v[58:61], v[206:209], v[214:217], v[58:61]
	v_mfma_i32_16x16x64_i8 v[54:57], v[198:201], v[226:229], v[54:57]
	v_mfma_i32_16x16x64_i8 v[50:53], v[206:209], v[226:229], v[50:53]
	v_mfma_i32_16x16x64_i8 v[46:49], v[198:201], v[234:237], v[46:49]
	v_mfma_i32_16x16x64_i8 v[42:45], v[206:209], v[234:237], v[42:45]
	v_mfma_i32_16x16x64_i8 v[38:41], v[198:201], v[242:245], v[38:41]
	v_mfma_i32_16x16x64_i8 v[34:37], v[206:209], v[242:245], v[34:37]
	v_mfma_i32_16x16x64_i8 v[62:65], v[202:205], v[222:225], v[62:65]
	v_mfma_i32_16x16x64_i8 v[58:61], v[210:213], v[222:225], v[58:61]
	v_mfma_i32_16x16x64_i8 v[54:57], v[202:205], v[230:233], v[54:57]
	v_mfma_i32_16x16x64_i8 v[50:53], v[210:213], v[230:233], v[50:53]
	v_mfma_i32_16x16x64_i8 v[46:49], v[202:205], v[238:241], v[46:49]
	v_mfma_i32_16x16x64_i8 v[42:45], v[210:213], v[238:241], v[42:45]
	v_mfma_i32_16x16x64_i8 v[38:41], v[202:205], v[246:249], v[38:41]
	v_mfma_i32_16x16x64_i8 v[34:37], v[210:213], v[246:249], v[34:37]
	s_barrier
	s_add_i32 s36, s38, s23
	v_lshl_add_u64 v[160:161], s[56:57], 0, v[162:163]
	s_mov_b32 m0, s36
	ds_read_b128 v[214:217], v189 offset:16384
	ds_read_b128 v[222:225], v189 offset:17408
	ds_read_b128 v[226:229], v189 offset:18432
	ds_read_b128 v[230:233], v189 offset:19456
	ds_read_b128 v[234:237], v189 offset:20480
	ds_read_b128 v[238:241], v189 offset:21504
	ds_read_b128 v[242:245], v189 offset:22528
	ds_read_b128 v[246:249], v189 offset:23552
	global_load_lds_dwordx4 v[160:161], off
	s_add_i32 m0, s36, 0x2000
	s_add_u32 s36, s56, 0x80000
	v_lshl_add_u64 v[250:251], s[56:57], 0, v[134:135]
	s_addc_u32 s37, s57, 0
	s_add_i32 s38, s39, s23
	global_load_lds_dwordx4 v[250:251], off
	v_lshl_add_u64 v[252:253], s[36:37], 0, v[162:163]
	s_mov_b32 m0, s38
	v_lshl_add_u64 v[168:169], s[58:59], 0, v[132:133]
	global_load_lds_dwordx4 v[252:253], off
	v_lshl_add_u64 v[252:253], s[36:37], 0, v[134:135]
	s_add_i32 m0, s38, 0x2000
	s_nop 0
	global_load_lds_dwordx4 v[252:253], off
	v_lshl_add_u64 v[252:253], s[58:59], 0, v[130:131]
	s_mov_b32 m0, s25
	s_nop 0
	global_load_lds_dwordx4 v[252:253], off
	s_mov_b32 m0, s67
	s_nop 0
	global_load_lds_dwordx4 v[168:169], off
	s_waitcnt vmcnt(8)
	s_waitcnt lgkmcnt(0)
	s_barrier
	v_mfma_i32_16x16x64_i8 v[94:97], v[156:159], v[214:217], v[94:97]
	v_mfma_i32_16x16x64_i8 v[90:93], v[190:193], v[214:217], v[90:93]
	v_mfma_i32_16x16x64_i8 v[86:89], v[156:159], v[226:229], v[86:89]
	v_mfma_i32_16x16x64_i8 v[82:85], v[190:193], v[226:229], v[82:85]
	v_mfma_i32_16x16x64_i8 v[78:81], v[156:159], v[234:237], v[78:81]
	v_mfma_i32_16x16x64_i8 v[74:77], v[190:193], v[234:237], v[74:77]
	v_mfma_i32_16x16x64_i8 v[70:73], v[156:159], v[242:245], v[70:73]
	v_mfma_i32_16x16x64_i8 v[66:69], v[190:193], v[242:245], v[66:69]
	v_mfma_i32_16x16x64_i8 v[94:97], v[172:175], v[222:225], v[94:97]
	v_mfma_i32_16x16x64_i8 v[90:93], v[194:197], v[222:225], v[90:93]
	v_mfma_i32_16x16x64_i8 v[86:89], v[172:175], v[230:233], v[86:89]
	v_mfma_i32_16x16x64_i8 v[82:85], v[194:197], v[230:233], v[82:85]
	v_mfma_i32_16x16x64_i8 v[78:81], v[172:175], v[238:241], v[78:81]
	v_mfma_i32_16x16x64_i8 v[74:77], v[194:197], v[238:241], v[74:77]
	v_mfma_i32_16x16x64_i8 v[70:73], v[172:175], v[246:249], v[70:73]
	v_mfma_i32_16x16x64_i8 v[66:69], v[194:197], v[246:249], v[66:69]
	v_mfma_i32_16x16x64_i8 v[30:33], v[198:201], v[214:217], v[30:33]
	v_mfma_i32_16x16x64_i8 v[26:29], v[206:209], v[214:217], v[26:29]
	v_mfma_i32_16x16x64_i8 v[22:25], v[198:201], v[226:229], v[22:25]
	v_mfma_i32_16x16x64_i8 v[18:21], v[206:209], v[226:229], v[18:21]
	v_mfma_i32_16x16x64_i8 v[14:17], v[198:201], v[234:237], v[14:17]
	v_mfma_i32_16x16x64_i8 v[10:13], v[206:209], v[234:237], v[10:13]
	v_mfma_i32_16x16x64_i8 v[6:9], v[198:201], v[242:245], v[6:9]
	v_mfma_i32_16x16x64_i8 v[2:5], v[206:209], v[242:245], v[2:5]
	v_mfma_i32_16x16x64_i8 v[30:33], v[202:205], v[222:225], v[30:33]
	v_mfma_i32_16x16x64_i8 v[26:29], v[210:213], v[222:225], v[26:29]
	v_mfma_i32_16x16x64_i8 v[22:25], v[202:205], v[230:233], v[22:25]
	v_mfma_i32_16x16x64_i8 v[18:21], v[210:213], v[230:233], v[18:21]
	v_mfma_i32_16x16x64_i8 v[14:17], v[202:205], v[238:241], v[14:17]
	v_mfma_i32_16x16x64_i8 v[10:13], v[210:213], v[238:241], v[10:13]
	v_mfma_i32_16x16x64_i8 v[6:9], v[202:205], v[246:249], v[6:9]
	v_mfma_i32_16x16x64_i8 v[2:5], v[210:213], v[246:249], v[2:5]
	s_barrier
	s_add_i32 s38, 0, 0x18000
	v_add_u32_e32 v140, s38, v149
	s_add_i32 s39, 0, 0x1c000
	ds_read_b128 v[156:159], v140
	ds_read_b128 v[172:175], v140 offset:1024
	ds_read_b128 v[190:193], v140 offset:2048
	ds_read_b128 v[194:197], v140 offset:3072
	v_add_u32_e32 v140, s39, v149
	ds_read_b128 v[198:201], v140
	ds_read_b128 v[202:205], v140 offset:1024
	ds_read_b128 v[206:209], v140 offset:2048
	ds_read_b128 v[210:213], v140 offset:3072
	s_add_u32 s36, s58, 0x40000
	s_addc_u32 s37, s59, 0
	s_mov_b32 m0, s68
	v_lshl_add_u64 v[170:171], s[36:37], 0, v[130:131]
	ds_read_b128 v[214:217], v189 offset:32768
	ds_read_b128 v[222:225], v189 offset:33792
	ds_read_b128 v[226:229], v189 offset:34816
	ds_read_b128 v[230:233], v189 offset:35840
	ds_read_b128 v[234:237], v189 offset:36864
	ds_read_b128 v[238:241], v189 offset:37888
	ds_read_b128 v[242:245], v189 offset:38912
	ds_read_b128 v[246:249], v189 offset:39936
	global_load_lds_dwordx4 v[170:171], off
	v_lshl_add_u64 v[170:171], s[36:37], 0, v[132:133]
	s_mov_b32 m0, s69
	s_nop 0
	global_load_lds_dwordx4 v[170:171], off
	s_waitcnt vmcnt(8)
	s_waitcnt lgkmcnt(0)
	s_barrier
	v_mfma_i32_16x16x64_i8 v[126:129], v[156:159], v[214:217], v[126:129]
	v_mfma_i32_16x16x64_i8 v[122:125], v[190:193], v[214:217], v[122:125]
	v_mfma_i32_16x16x64_i8 v[118:121], v[156:159], v[226:229], v[118:121]
	v_mfma_i32_16x16x64_i8 v[114:117], v[190:193], v[226:229], v[114:117]
	v_mfma_i32_16x16x64_i8 v[110:113], v[156:159], v[234:237], v[110:113]
	v_mfma_i32_16x16x64_i8 v[106:109], v[190:193], v[234:237], v[106:109]
	v_mfma_i32_16x16x64_i8 v[102:105], v[156:159], v[242:245], v[102:105]
	v_mfma_i32_16x16x64_i8 v[98:101], v[190:193], v[242:245], v[98:101]
	v_mfma_i32_16x16x64_i8 v[126:129], v[172:175], v[222:225], v[126:129]
	v_mfma_i32_16x16x64_i8 v[122:125], v[194:197], v[222:225], v[122:125]
	v_mfma_i32_16x16x64_i8 v[118:121], v[172:175], v[230:233], v[118:121]
	v_mfma_i32_16x16x64_i8 v[114:117], v[194:197], v[230:233], v[114:117]
	v_mfma_i32_16x16x64_i8 v[110:113], v[172:175], v[238:241], v[110:113]
	v_mfma_i32_16x16x64_i8 v[106:109], v[194:197], v[238:241], v[106:109]
	v_mfma_i32_16x16x64_i8 v[102:105], v[172:175], v[246:249], v[102:105]
	v_mfma_i32_16x16x64_i8 v[98:101], v[194:197], v[246:249], v[98:101]
	v_mfma_i32_16x16x64_i8 v[62:65], v[198:201], v[214:217], v[62:65]
	v_mfma_i32_16x16x64_i8 v[58:61], v[206:209], v[214:217], v[58:61]
	v_mfma_i32_16x16x64_i8 v[54:57], v[198:201], v[226:229], v[54:57]
	v_mfma_i32_16x16x64_i8 v[50:53], v[206:209], v[226:229], v[50:53]
	v_mfma_i32_16x16x64_i8 v[46:49], v[198:201], v[234:237], v[46:49]
	v_mfma_i32_16x16x64_i8 v[42:45], v[206:209], v[234:237], v[42:45]
	v_mfma_i32_16x16x64_i8 v[38:41], v[198:201], v[242:245], v[38:41]
	v_mfma_i32_16x16x64_i8 v[34:37], v[206:209], v[242:245], v[34:37]
	v_mfma_i32_16x16x64_i8 v[62:65], v[202:205], v[222:225], v[62:65]
	v_mfma_i32_16x16x64_i8 v[58:61], v[210:213], v[222:225], v[58:61]
	v_mfma_i32_16x16x64_i8 v[54:57], v[202:205], v[230:233], v[54:57]
	v_mfma_i32_16x16x64_i8 v[50:53], v[210:213], v[230:233], v[50:53]
	v_mfma_i32_16x16x64_i8 v[46:49], v[202:205], v[238:241], v[46:49]
	v_mfma_i32_16x16x64_i8 v[42:45], v[210:213], v[238:241], v[42:45]
	v_mfma_i32_16x16x64_i8 v[38:41], v[202:205], v[246:249], v[38:41]
	v_mfma_i32_16x16x64_i8 v[34:37], v[210:213], v[246:249], v[34:37]
	s_barrier
	s_add_i32 s36, s38, s23
	v_lshl_add_u64 v[160:161], v[160:161], 0, s[44:45]
	s_mov_b32 m0, s36
	ds_read_b128 v[214:217], v189 offset:49152
	ds_read_b128 v[222:225], v189 offset:50176
	ds_read_b128 v[226:229], v189 offset:51200
	ds_read_b128 v[230:233], v189 offset:52224
	ds_read_b128 v[234:237], v189 offset:53248
	ds_read_b128 v[238:241], v189 offset:54272
	ds_read_b128 v[242:245], v189 offset:55296
	ds_read_b128 v[246:249], v189 offset:56320
	global_load_lds_dwordx4 v[160:161], off
	s_add_i32 m0, s36, 0x2000
	s_add_u32 s36, s56, 0x80080
	v_lshl_add_u64 v[160:161], v[250:251], 0, s[44:45]
	s_addc_u32 s37, s57, 0
	s_add_i32 s38, s39, s23
	global_load_lds_dwordx4 v[160:161], off
	v_lshl_add_u64 v[160:161], s[36:37], 0, v[162:163]
	s_mov_b32 m0, s38
	s_nop 0
	global_load_lds_dwordx4 v[160:161], off
	v_lshl_add_u64 v[160:161], s[36:37], 0, v[134:135]
	s_add_i32 m0, s38, 0x2000
	s_nop 0
	global_load_lds_dwordx4 v[160:161], off
	v_lshl_add_u64 v[160:161], v[252:253], 0, s[44:45]
	s_mov_b32 m0, s71
	s_nop 0
	global_load_lds_dwordx4 v[160:161], off
	v_lshl_add_u64 v[160:161], v[168:169], 0, s[44:45]
	s_mov_b32 m0, s72
	s_nop 0
	global_load_lds_dwordx4 v[160:161], off
	s_waitcnt vmcnt(8)
	s_waitcnt lgkmcnt(0)
	s_barrier
	v_mfma_i32_16x16x64_i8 v[94:97], v[156:159], v[214:217], v[94:97]
	v_mfma_i32_16x16x64_i8 v[90:93], v[190:193], v[214:217], v[90:93]
	s_add_i32 s60, s60, 2
	v_mfma_i32_16x16x64_i8 v[86:89], v[156:159], v[226:229], v[86:89]
	s_add_u32 s15, s15, 0x100
	v_mfma_i32_16x16x64_i8 v[82:85], v[190:193], v[226:229], v[82:85]
	s_addc_u32 s17, s17, 0
	v_mfma_i32_16x16x64_i8 v[78:81], v[156:159], v[234:237], v[78:81]
	s_add_u32 s26, s26, 0x100
	v_mfma_i32_16x16x64_i8 v[74:77], v[190:193], v[234:237], v[74:77]
	s_addc_u32 s27, s27, 0
	v_mfma_i32_16x16x64_i8 v[70:73], v[156:159], v[242:245], v[70:73]
	s_cmp_gt_u32 s60, 13
	v_mfma_i32_16x16x64_i8 v[66:69], v[190:193], v[242:245], v[66:69]
	v_mfma_i32_16x16x64_i8 v[94:97], v[172:175], v[222:225], v[94:97]
	v_mfma_i32_16x16x64_i8 v[90:93], v[194:197], v[222:225], v[90:93]
	v_mfma_i32_16x16x64_i8 v[86:89], v[172:175], v[230:233], v[86:89]
	v_mfma_i32_16x16x64_i8 v[82:85], v[194:197], v[230:233], v[82:85]
	v_mfma_i32_16x16x64_i8 v[78:81], v[172:175], v[238:241], v[78:81]
	v_mfma_i32_16x16x64_i8 v[74:77], v[194:197], v[238:241], v[74:77]
	v_mfma_i32_16x16x64_i8 v[70:73], v[172:175], v[246:249], v[70:73]
	v_mfma_i32_16x16x64_i8 v[66:69], v[194:197], v[246:249], v[66:69]
	v_mfma_i32_16x16x64_i8 v[30:33], v[198:201], v[214:217], v[30:33]
	v_mfma_i32_16x16x64_i8 v[26:29], v[206:209], v[214:217], v[26:29]
	v_mfma_i32_16x16x64_i8 v[22:25], v[198:201], v[226:229], v[22:25]
	v_mfma_i32_16x16x64_i8 v[18:21], v[206:209], v[226:229], v[18:21]
	v_mfma_i32_16x16x64_i8 v[14:17], v[198:201], v[234:237], v[14:17]
	v_mfma_i32_16x16x64_i8 v[10:13], v[206:209], v[234:237], v[10:13]
	v_mfma_i32_16x16x64_i8 v[6:9], v[198:201], v[242:245], v[6:9]
	v_mfma_i32_16x16x64_i8 v[2:5], v[206:209], v[242:245], v[2:5]
	v_mfma_i32_16x16x64_i8 v[30:33], v[202:205], v[222:225], v[30:33]
	v_mfma_i32_16x16x64_i8 v[26:29], v[210:213], v[222:225], v[26:29]
	v_mfma_i32_16x16x64_i8 v[22:25], v[202:205], v[230:233], v[22:25]
	v_mfma_i32_16x16x64_i8 v[18:21], v[210:213], v[230:233], v[18:21]
	v_mfma_i32_16x16x64_i8 v[14:17], v[202:205], v[238:241], v[14:17]
	v_mfma_i32_16x16x64_i8 v[10:13], v[210:213], v[238:241], v[10:13]
	v_mfma_i32_16x16x64_i8 v[6:9], v[202:205], v[246:249], v[6:9]
	v_mfma_i32_16x16x64_i8 v[2:5], v[210:213], v[246:249], v[2:5]
	s_barrier
	s_cbranch_scc0 .LBB0_696
	s_and_b64 vcc, exec, s[12:13]
	s_cbranch_vccz .LBB0_699
	s_barrier

.LBB0_968:
	s_add_i32 s76, s24, 2
	s_add_u32 s25, s22, 0xfff80080
	s_addc_u32 s26, s23, -1
	s_add_i32 s36, 0, 0x10000
	s_cmp_eq_u32 s56, s24
	s_cselect_b32 s27, s19, s26
	s_cselect_b32 s26, s18, s25
	s_cselect_b32 s25, s21, s75
	s_cselect_b32 s24, s20, s74
	s_add_i32 s38, 0, 0x14000
	v_add_u32_e32 v152, s36, v211
	v_add_u32_e32 v160, s38, v211
	ds_read_b128 v[140:143], v152
	ds_read_b128 v[144:147], v152 offset:1024
	ds_read_b128 v[148:151], v152 offset:2048
	ds_read_b128 v[152:155], v152 offset:3072
	ds_read_b128 v[156:159], v160
	ds_read_b128 v[172:175], v160 offset:1024
	ds_read_b128 v[176:179], v160 offset:2048
	ds_read_b128 v[180:183], v160 offset:3072
	v_lshl_add_u64 v[160:161], s[22:23], 0, v[138:139]
	s_add_i32 m0, s61, 0xc000
	ds_read_b128 v[184:187], v213
	ds_read_b128 v[188:191], v213 offset:1024
	ds_read_b128 v[192:195], v213 offset:2048
	ds_read_b128 v[196:199], v213 offset:3072
	ds_read_b128 v[200:203], v213 offset:4096
	ds_read_b128 v[204:207], v213 offset:5120
	ds_read_b128 v[222:225], v213 offset:6144
	ds_read_b128 v[226:229], v213 offset:7168
	global_load_lds_dwordx4 v[160:161], off
	v_lshl_add_u64 v[160:161], s[22:23], 0, v[136:137]
	s_add_i32 m0, s61, 0xe000
	s_nop 0
	global_load_lds_dwordx4 v[160:161], off
	s_waitcnt vmcnt(8)
	s_waitcnt lgkmcnt(0)
	s_barrier
	v_mfma_f32_16x16x32_bf16 v[126:129], v[140:143], v[184:187], v[126:129]
	v_mfma_f32_16x16x32_bf16 v[122:125], v[148:151], v[184:187], v[122:125]
	v_mfma_f32_16x16x32_bf16 v[118:121], v[140:143], v[192:195], v[118:121]
	v_mfma_f32_16x16x32_bf16 v[114:117], v[148:151], v[192:195], v[114:117]
	v_mfma_f32_16x16x32_bf16 v[110:113], v[140:143], v[200:203], v[110:113]
	v_mfma_f32_16x16x32_bf16 v[106:109], v[148:151], v[200:203], v[106:109]
	v_mfma_f32_16x16x32_bf16 v[102:105], v[140:143], v[222:225], v[102:105]
	v_mfma_f32_16x16x32_bf16 v[98:101], v[148:151], v[222:225], v[98:101]
	v_mfma_f32_16x16x32_bf16 v[126:129], v[144:147], v[188:191], v[126:129]
	v_mfma_f32_16x16x32_bf16 v[122:125], v[152:155], v[188:191], v[122:125]
	v_mfma_f32_16x16x32_bf16 v[118:121], v[144:147], v[196:199], v[118:121]
	v_mfma_f32_16x16x32_bf16 v[114:117], v[152:155], v[196:199], v[114:117]
	v_mfma_f32_16x16x32_bf16 v[110:113], v[144:147], v[204:207], v[110:113]
	v_mfma_f32_16x16x32_bf16 v[106:109], v[152:155], v[204:207], v[106:109]
	v_mfma_f32_16x16x32_bf16 v[102:105], v[144:147], v[226:229], v[102:105]
	v_mfma_f32_16x16x32_bf16 v[98:101], v[152:155], v[226:229], v[98:101]
	v_mfma_f32_16x16x32_bf16 v[94:97], v[156:159], v[184:187], v[94:97]
	v_mfma_f32_16x16x32_bf16 v[90:93], v[176:179], v[184:187], v[90:93]
	v_mfma_f32_16x16x32_bf16 v[86:89], v[156:159], v[192:195], v[86:89]
	v_mfma_f32_16x16x32_bf16 v[82:85], v[176:179], v[192:195], v[82:85]
	v_mfma_f32_16x16x32_bf16 v[78:81], v[156:159], v[200:203], v[78:81]
	v_mfma_f32_16x16x32_bf16 v[74:77], v[176:179], v[200:203], v[74:77]
	v_mfma_f32_16x16x32_bf16 v[70:73], v[156:159], v[222:225], v[70:73]
	v_mfma_f32_16x16x32_bf16 v[66:69], v[176:179], v[222:225], v[66:69]
	v_mfma_f32_16x16x32_bf16 v[94:97], v[172:175], v[188:191], v[94:97]
	v_mfma_f32_16x16x32_bf16 v[90:93], v[180:183], v[188:191], v[90:93]
	v_mfma_f32_16x16x32_bf16 v[86:89], v[172:175], v[196:199], v[86:89]
	v_mfma_f32_16x16x32_bf16 v[82:85], v[180:183], v[196:199], v[82:85]
	v_mfma_f32_16x16x32_bf16 v[78:81], v[172:175], v[204:207], v[78:81]
	v_mfma_f32_16x16x32_bf16 v[74:77], v[180:183], v[204:207], v[74:77]
	v_mfma_f32_16x16x32_bf16 v[70:73], v[172:175], v[226:229], v[70:73]
	v_mfma_f32_16x16x32_bf16 v[66:69], v[180:183], v[226:229], v[66:69]
	s_barrier
	s_add_i32 s36, s36, s60
	v_lshl_add_u64 v[160:161], s[24:25], 0, v[162:163]
	s_mov_b32 m0, s36
	ds_read_b128 v[184:187], v213 offset:16384
	ds_read_b128 v[188:191], v213 offset:17408
	ds_read_b128 v[192:195], v213 offset:18432
	ds_read_b128 v[196:199], v213 offset:19456
	ds_read_b128 v[200:203], v213 offset:20480
	ds_read_b128 v[204:207], v213 offset:21504
	ds_read_b128 v[222:225], v213 offset:22528
	ds_read_b128 v[226:229], v213 offset:23552
	global_load_lds_dwordx4 v[160:161], off
	s_add_i32 m0, s36, 0x2000
	s_add_u32 s36, s24, 0x80000
	v_lshl_add_u64 v[168:169], s[24:25], 0, v[134:135]
	s_addc_u32 s37, s25, 0
	s_add_i32 s38, s38, s60
	global_load_lds_dwordx4 v[168:169], off
	v_lshl_add_u64 v[170:171], s[36:37], 0, v[162:163]
	s_mov_b32 m0, s38
	v_lshl_add_u64 v[208:209], s[26:27], 0, v[132:133]
	global_load_lds_dwordx4 v[170:171], off
	v_lshl_add_u64 v[170:171], s[36:37], 0, v[134:135]
	s_add_i32 m0, s38, 0x2000
	s_nop 0
	global_load_lds_dwordx4 v[170:171], off
	v_lshl_add_u64 v[170:171], s[26:27], 0, v[130:131]
	s_mov_b32 m0, s61
	s_nop 0
	global_load_lds_dwordx4 v[170:171], off
	s_mov_b32 m0, s62
	s_nop 0
	global_load_lds_dwordx4 v[208:209], off
	s_waitcnt vmcnt(8)
	s_waitcnt lgkmcnt(0)
	s_barrier
	v_mfma_f32_16x16x32_bf16 v[62:65], v[140:143], v[184:187], v[62:65]
	v_mfma_f32_16x16x32_bf16 v[58:61], v[148:151], v[184:187], v[58:61]
	v_mfma_f32_16x16x32_bf16 v[54:57], v[140:143], v[192:195], v[54:57]
	v_mfma_f32_16x16x32_bf16 v[50:53], v[148:151], v[192:195], v[50:53]
	v_mfma_f32_16x16x32_bf16 v[46:49], v[140:143], v[200:203], v[46:49]
	v_mfma_f32_16x16x32_bf16 v[42:45], v[148:151], v[200:203], v[42:45]
	v_mfma_f32_16x16x32_bf16 v[38:41], v[140:143], v[222:225], v[38:41]
	v_mfma_f32_16x16x32_bf16 v[34:37], v[148:151], v[222:225], v[34:37]
	v_mfma_f32_16x16x32_bf16 v[62:65], v[144:147], v[188:191], v[62:65]
	v_mfma_f32_16x16x32_bf16 v[58:61], v[152:155], v[188:191], v[58:61]
	v_mfma_f32_16x16x32_bf16 v[54:57], v[144:147], v[196:199], v[54:57]
	v_mfma_f32_16x16x32_bf16 v[50:53], v[152:155], v[196:199], v[50:53]
	v_mfma_f32_16x16x32_bf16 v[46:49], v[144:147], v[204:207], v[46:49]
	v_mfma_f32_16x16x32_bf16 v[42:45], v[152:155], v[204:207], v[42:45]
	v_mfma_f32_16x16x32_bf16 v[38:41], v[144:147], v[226:229], v[38:41]
	v_mfma_f32_16x16x32_bf16 v[34:37], v[152:155], v[226:229], v[34:37]
	v_mfma_f32_16x16x32_bf16 v[30:33], v[156:159], v[184:187], v[30:33]
	v_mfma_f32_16x16x32_bf16 v[26:29], v[176:179], v[184:187], v[26:29]
	v_mfma_f32_16x16x32_bf16 v[22:25], v[156:159], v[192:195], v[22:25]
	v_mfma_f32_16x16x32_bf16 v[18:21], v[176:179], v[192:195], v[18:21]
	v_mfma_f32_16x16x32_bf16 v[14:17], v[156:159], v[200:203], v[14:17]
	v_mfma_f32_16x16x32_bf16 v[10:13], v[176:179], v[200:203], v[10:13]
	v_mfma_f32_16x16x32_bf16 v[6:9], v[156:159], v[222:225], v[6:9]
	v_mfma_f32_16x16x32_bf16 v[2:5], v[176:179], v[222:225], v[2:5]
	v_mfma_f32_16x16x32_bf16 v[30:33], v[172:175], v[188:191], v[30:33]
	v_mfma_f32_16x16x32_bf16 v[26:29], v[180:183], v[188:191], v[26:29]
	v_mfma_f32_16x16x32_bf16 v[22:25], v[172:175], v[196:199], v[22:25]
	v_mfma_f32_16x16x32_bf16 v[18:21], v[180:183], v[196:199], v[18:21]
	v_mfma_f32_16x16x32_bf16 v[14:17], v[172:175], v[204:207], v[14:17]
	v_mfma_f32_16x16x32_bf16 v[10:13], v[180:183], v[204:207], v[10:13]
	v_mfma_f32_16x16x32_bf16 v[6:9], v[172:175], v[226:229], v[6:9]
	v_mfma_f32_16x16x32_bf16 v[2:5], v[180:183], v[226:229], v[2:5]
	s_barrier
	s_add_i32 s36, 0, 0x18000
	s_add_i32 s37, 0, 0x1c000
	v_add_u32_e32 v152, s36, v211
	v_add_u32_e32 v180, s37, v211
	ds_read_b128 v[140:143], v152
	ds_read_b128 v[144:147], v152 offset:1024
	ds_read_b128 v[148:151], v152 offset:2048
	ds_read_b128 v[152:155], v152 offset:3072
	ds_read_b128 v[156:159], v180
	ds_read_b128 v[172:175], v180 offset:1024
	ds_read_b128 v[176:179], v180 offset:2048
	ds_read_b128 v[180:183], v180 offset:3072
	s_add_u32 s26, s26, 0x80000
	s_addc_u32 s27, s27, 0
	s_mov_b32 m0, s63
	v_lshl_add_u64 v[216:217], s[26:27], 0, v[130:131]
	ds_read_b128 v[184:187], v213 offset:32768
	ds_read_b128 v[188:191], v213 offset:33792
	ds_read_b128 v[192:195], v213 offset:34816
	ds_read_b128 v[196:199], v213 offset:35840
	ds_read_b128 v[200:203], v213 offset:36864
	ds_read_b128 v[204:207], v213 offset:37888
	ds_read_b128 v[222:225], v213 offset:38912
	ds_read_b128 v[226:229], v213 offset:39936
	global_load_lds_dwordx4 v[216:217], off
	v_lshl_add_u64 v[216:217], s[26:27], 0, v[132:133]
	s_mov_b32 m0, s64
	s_nop 0
	global_load_lds_dwordx4 v[216:217], off
	s_waitcnt vmcnt(8)
	s_waitcnt lgkmcnt(0)
	s_barrier
	v_mfma_f32_16x16x32_bf16 v[126:129], v[140:143], v[184:187], v[126:129]
	v_mfma_f32_16x16x32_bf16 v[122:125], v[148:151], v[184:187], v[122:125]
	v_mfma_f32_16x16x32_bf16 v[118:121], v[140:143], v[192:195], v[118:121]
	v_mfma_f32_16x16x32_bf16 v[114:117], v[148:151], v[192:195], v[114:117]
	v_mfma_f32_16x16x32_bf16 v[110:113], v[140:143], v[200:203], v[110:113]
	v_mfma_f32_16x16x32_bf16 v[106:109], v[148:151], v[200:203], v[106:109]
	v_mfma_f32_16x16x32_bf16 v[102:105], v[140:143], v[222:225], v[102:105]
	v_mfma_f32_16x16x32_bf16 v[98:101], v[148:151], v[222:225], v[98:101]
	v_mfma_f32_16x16x32_bf16 v[126:129], v[144:147], v[188:191], v[126:129]
	v_mfma_f32_16x16x32_bf16 v[122:125], v[152:155], v[188:191], v[122:125]
	v_mfma_f32_16x16x32_bf16 v[118:121], v[144:147], v[196:199], v[118:121]
	v_mfma_f32_16x16x32_bf16 v[114:117], v[152:155], v[196:199], v[114:117]
	v_mfma_f32_16x16x32_bf16 v[110:113], v[144:147], v[204:207], v[110:113]
	v_mfma_f32_16x16x32_bf16 v[106:109], v[152:155], v[204:207], v[106:109]
	v_mfma_f32_16x16x32_bf16 v[102:105], v[144:147], v[226:229], v[102:105]
	v_mfma_f32_16x16x32_bf16 v[98:101], v[152:155], v[226:229], v[98:101]
	v_mfma_f32_16x16x32_bf16 v[94:97], v[156:159], v[184:187], v[94:97]
	v_mfma_f32_16x16x32_bf16 v[90:93], v[176:179], v[184:187], v[90:93]
	v_mfma_f32_16x16x32_bf16 v[86:89], v[156:159], v[192:195], v[86:89]
	v_mfma_f32_16x16x32_bf16 v[82:85], v[176:179], v[192:195], v[82:85]
	v_mfma_f32_16x16x32_bf16 v[78:81], v[156:159], v[200:203], v[78:81]
	v_mfma_f32_16x16x32_bf16 v[74:77], v[176:179], v[200:203], v[74:77]
	v_mfma_f32_16x16x32_bf16 v[70:73], v[156:159], v[222:225], v[70:73]
	v_mfma_f32_16x16x32_bf16 v[66:69], v[176:179], v[222:225], v[66:69]
	v_mfma_f32_16x16x32_bf16 v[94:97], v[172:175], v[188:191], v[94:97]
	v_mfma_f32_16x16x32_bf16 v[90:93], v[180:183], v[188:191], v[90:93]
	v_mfma_f32_16x16x32_bf16 v[86:89], v[172:175], v[196:199], v[86:89]
	v_mfma_f32_16x16x32_bf16 v[82:85], v[180:183], v[196:199], v[82:85]
	v_mfma_f32_16x16x32_bf16 v[78:81], v[172:175], v[204:207], v[78:81]
	v_mfma_f32_16x16x32_bf16 v[74:77], v[180:183], v[204:207], v[74:77]
	v_mfma_f32_16x16x32_bf16 v[70:73], v[172:175], v[226:229], v[70:73]
	v_mfma_f32_16x16x32_bf16 v[66:69], v[180:183], v[226:229], v[66:69]
	s_barrier
	s_add_i32 s26, s36, s60
	v_lshl_add_u64 v[160:161], v[160:161], 0, s[44:45]
	s_mov_b32 m0, s26
	ds_read_b128 v[184:187], v213 offset:49152
	ds_read_b128 v[188:191], v213 offset:50176
	ds_read_b128 v[192:195], v213 offset:51200
	ds_read_b128 v[196:199], v213 offset:52224
	ds_read_b128 v[200:203], v213 offset:53248
	ds_read_b128 v[204:207], v213 offset:54272
	ds_read_b128 v[222:225], v213 offset:55296
	ds_read_b128 v[226:229], v213 offset:56320
	global_load_lds_dwordx4 v[160:161], off
	s_add_i32 m0, s26, 0x2000
	s_add_u32 s24, s24, 0x80080
	v_lshl_add_u64 v[160:161], v[168:169], 0, s[44:45]
	s_addc_u32 s25, s25, 0
	s_add_i32 s26, s37, s60
	global_load_lds_dwordx4 v[160:161], off
	v_lshl_add_u64 v[160:161], s[24:25], 0, v[162:163]
	s_mov_b32 m0, s26
	s_nop 0
	global_load_lds_dwordx4 v[160:161], off
	v_lshl_add_u64 v[160:161], s[24:25], 0, v[134:135]
	s_add_i32 m0, s26, 0x2000
	s_nop 0
	global_load_lds_dwordx4 v[160:161], off
	v_lshl_add_u64 v[160:161], v[170:171], 0, s[44:45]
	s_mov_b32 m0, s65
	s_nop 0
	global_load_lds_dwordx4 v[160:161], off
	v_lshl_add_u64 v[160:161], v[208:209], 0, s[44:45]
	s_mov_b32 m0, s66
	s_nop 0
	global_load_lds_dwordx4 v[160:161], off
	s_waitcnt vmcnt(8)
	s_waitcnt lgkmcnt(0)
	s_barrier
	v_mfma_f32_16x16x32_bf16 v[62:65], v[140:143], v[184:187], v[62:65]
	v_mfma_f32_16x16x32_bf16 v[58:61], v[148:151], v[184:187], v[58:61]
	s_add_u32 s74, s74, 0x100
	v_mfma_f32_16x16x32_bf16 v[54:57], v[140:143], v[192:195], v[54:57]
	s_addc_u32 s75, s75, 0
	v_mfma_f32_16x16x32_bf16 v[50:53], v[148:151], v[192:195], v[50:53]
	s_add_u32 s22, s22, 0x100
	v_mfma_f32_16x16x32_bf16 v[46:49], v[140:143], v[200:203], v[46:49]
	s_addc_u32 s23, s23, 0
	v_mfma_f32_16x16x32_bf16 v[42:45], v[148:151], v[200:203], v[42:45]
	s_cmp_ge_i32 s76, s9
	v_mfma_f32_16x16x32_bf16 v[38:41], v[140:143], v[222:225], v[38:41]
	s_mov_b32 s24, s76
	v_mfma_f32_16x16x32_bf16 v[34:37], v[148:151], v[222:225], v[34:37]
	v_mfma_f32_16x16x32_bf16 v[62:65], v[144:147], v[188:191], v[62:65]
	v_mfma_f32_16x16x32_bf16 v[58:61], v[152:155], v[188:191], v[58:61]
	v_mfma_f32_16x16x32_bf16 v[54:57], v[144:147], v[196:199], v[54:57]
	v_mfma_f32_16x16x32_bf16 v[50:53], v[152:155], v[196:199], v[50:53]
	v_mfma_f32_16x16x32_bf16 v[46:49], v[144:147], v[204:207], v[46:49]
	v_mfma_f32_16x16x32_bf16 v[42:45], v[152:155], v[204:207], v[42:45]
	v_mfma_f32_16x16x32_bf16 v[38:41], v[144:147], v[226:229], v[38:41]
	v_mfma_f32_16x16x32_bf16 v[34:37], v[152:155], v[226:229], v[34:37]
	v_mfma_f32_16x16x32_bf16 v[30:33], v[156:159], v[184:187], v[30:33]
	v_mfma_f32_16x16x32_bf16 v[26:29], v[176:179], v[184:187], v[26:29]
	v_mfma_f32_16x16x32_bf16 v[22:25], v[156:159], v[192:195], v[22:25]
	v_mfma_f32_16x16x32_bf16 v[18:21], v[176:179], v[192:195], v[18:21]
	v_mfma_f32_16x16x32_bf16 v[14:17], v[156:159], v[200:203], v[14:17]
	v_mfma_f32_16x16x32_bf16 v[10:13], v[176:179], v[200:203], v[10:13]
	v_mfma_f32_16x16x32_bf16 v[6:9], v[156:159], v[222:225], v[6:9]
	v_mfma_f32_16x16x32_bf16 v[2:5], v[176:179], v[222:225], v[2:5]
	v_mfma_f32_16x16x32_bf16 v[30:33], v[172:175], v[188:191], v[30:33]
	v_mfma_f32_16x16x32_bf16 v[26:29], v[180:183], v[188:191], v[26:29]
	v_mfma_f32_16x16x32_bf16 v[22:25], v[172:175], v[196:199], v[22:25]
	v_mfma_f32_16x16x32_bf16 v[18:21], v[180:183], v[196:199], v[18:21]
	v_mfma_f32_16x16x32_bf16 v[14:17], v[172:175], v[204:207], v[14:17]
	v_mfma_f32_16x16x32_bf16 v[10:13], v[180:183], v[204:207], v[10:13]
	v_mfma_f32_16x16x32_bf16 v[6:9], v[172:175], v[226:229], v[6:9]
	v_mfma_f32_16x16x32_bf16 v[2:5], v[180:183], v[226:229], v[2:5]
	s_barrier
	s_cbranch_scc0 .LBB0_968
	s_and_b64 vcc, exec, s[14:15]
	s_cbranch_vccz .LBB0_971
	s_barrier

.LBB0_1211:
	s_add_u32 s36, s56, 0xfff80080
	s_addc_u32 s37, s57, -1
	s_add_i32 s38, 0, 0x10000
	s_cmp_eq_u32 s78, 28
	s_cselect_b32 s61, s21, s37
	s_cselect_b32 s60, s20, s36
	s_cselect_b32 s59, s23, s62
	s_cselect_b32 s58, s22, s25
	s_add_i32 s39, 0, 0x14000
	v_add_u32_e32 v142, s38, v201
	v_add_u32_e32 v168, s39, v201
	ds_read_b128 v[110:113], v142
	ds_read_b128 v[118:121], v142 offset:1024
	ds_read_b128 v[138:141], v142 offset:2048
	ds_read_b128 v[142:145], v142 offset:3072
	ds_read_b128 v[146:149], v168
	ds_read_b128 v[150:153], v168 offset:1024
	ds_read_b128 v[174:177], v168 offset:2048
	ds_read_b128 v[178:181], v168 offset:3072
	v_lshl_add_u64 v[168:169], s[56:57], 0, v[172:173]
	s_add_i32 m0, s66, 0xc000
	ds_read_b128 v[182:185], v203
	ds_read_b128 v[186:189], v203 offset:1024
	ds_read_b128 v[190:193], v203 offset:2048
	ds_read_b128 v[194:197], v203 offset:3072
	ds_read_b128 v[204:207], v203 offset:4096
	ds_read_b128 v[208:211], v203 offset:5120
	ds_read_b128 v[212:215], v203 offset:6144
	ds_read_b128 v[222:225], v203 offset:7168
	global_load_lds_dwordx4 v[168:169], off
	v_lshl_add_u64 v[168:169], s[56:57], 0, v[160:161]
	s_add_i32 m0, s66, 0xe000
	s_nop 0
	global_load_lds_dwordx4 v[168:169], off
	s_waitcnt vmcnt(8)
	s_waitcnt lgkmcnt(0)
	s_barrier
	v_mfma_f32_16x16x32_bf16 v[134:137], v[110:113], v[182:185], v[134:137]
	v_mfma_f32_16x16x32_bf16 v[130:133], v[138:141], v[182:185], v[130:133]
	v_mfma_f32_16x16x32_bf16 v[114:117], v[110:113], v[190:193], v[114:117]
	v_mfma_f32_16x16x32_bf16 v[106:109], v[138:141], v[190:193], v[106:109]
	v_mfma_f32_16x16x32_bf16 v[94:97], v[110:113], v[204:207], v[94:97]
	v_mfma_f32_16x16x32_bf16 v[90:93], v[138:141], v[204:207], v[90:93]
	v_mfma_f32_16x16x32_bf16 v[78:81], v[110:113], v[212:215], v[78:81]
	v_mfma_f32_16x16x32_bf16 v[74:77], v[138:141], v[212:215], v[74:77]
	v_mfma_f32_16x16x32_bf16 v[134:137], v[118:121], v[186:189], v[134:137]
	v_mfma_f32_16x16x32_bf16 v[130:133], v[142:145], v[186:189], v[130:133]
	v_mfma_f32_16x16x32_bf16 v[114:117], v[118:121], v[194:197], v[114:117]
	v_mfma_f32_16x16x32_bf16 v[106:109], v[142:145], v[194:197], v[106:109]
	v_mfma_f32_16x16x32_bf16 v[94:97], v[118:121], v[208:211], v[94:97]
	v_mfma_f32_16x16x32_bf16 v[90:93], v[142:145], v[208:211], v[90:93]
	v_mfma_f32_16x16x32_bf16 v[78:81], v[118:121], v[222:225], v[78:81]
	v_mfma_f32_16x16x32_bf16 v[74:77], v[142:145], v[222:225], v[74:77]
	v_mfma_f32_16x16x32_bf16 v[126:129], v[146:149], v[182:185], v[126:129]
	v_mfma_f32_16x16x32_bf16 v[122:125], v[174:177], v[182:185], v[122:125]
	v_mfma_f32_16x16x32_bf16 v[102:105], v[146:149], v[190:193], v[102:105]
	v_mfma_f32_16x16x32_bf16 v[98:101], v[174:177], v[190:193], v[98:101]
	v_mfma_f32_16x16x32_bf16 v[86:89], v[146:149], v[204:207], v[86:89]
	v_mfma_f32_16x16x32_bf16 v[82:85], v[174:177], v[204:207], v[82:85]
	v_mfma_f32_16x16x32_bf16 v[70:73], v[146:149], v[212:215], v[70:73]
	v_mfma_f32_16x16x32_bf16 v[66:69], v[174:177], v[212:215], v[66:69]
	v_mfma_f32_16x16x32_bf16 v[126:129], v[150:153], v[186:189], v[126:129]
	v_mfma_f32_16x16x32_bf16 v[122:125], v[178:181], v[186:189], v[122:125]
	v_mfma_f32_16x16x32_bf16 v[102:105], v[150:153], v[194:197], v[102:105]
	v_mfma_f32_16x16x32_bf16 v[98:101], v[178:181], v[194:197], v[98:101]
	v_mfma_f32_16x16x32_bf16 v[86:89], v[150:153], v[208:211], v[86:89]
	v_mfma_f32_16x16x32_bf16 v[82:85], v[178:181], v[208:211], v[82:85]
	v_mfma_f32_16x16x32_bf16 v[70:73], v[150:153], v[222:225], v[70:73]
	v_mfma_f32_16x16x32_bf16 v[66:69], v[178:181], v[222:225], v[66:69]
	s_barrier
	s_add_i32 s36, s38, s27
	v_lshl_add_u64 v[168:169], s[58:59], 0, v[162:163]
	s_mov_b32 m0, s36
	ds_read_b128 v[182:185], v203 offset:16384
	ds_read_b128 v[186:189], v203 offset:17408
	ds_read_b128 v[190:193], v203 offset:18432
	ds_read_b128 v[194:197], v203 offset:19456
	ds_read_b128 v[204:207], v203 offset:20480
	ds_read_b128 v[208:211], v203 offset:21504
	ds_read_b128 v[212:215], v203 offset:22528
	ds_read_b128 v[222:225], v203 offset:23552
	global_load_lds_dwordx4 v[168:169], off
	s_add_i32 m0, s36, 0x2000
	s_add_u32 s36, s58, 0x80000
	v_lshl_add_u64 v[170:171], s[58:59], 0, v[158:159]
	s_addc_u32 s37, s59, 0
	s_add_i32 s38, s39, s27
	global_load_lds_dwordx4 v[170:171], off
	v_lshl_add_u64 v[198:199], s[36:37], 0, v[162:163]
	s_mov_b32 m0, s38
	v_lshl_add_u64 v[216:217], s[60:61], 0, v[156:157]
	global_load_lds_dwordx4 v[198:199], off
	v_lshl_add_u64 v[198:199], s[36:37], 0, v[158:159]
	s_add_i32 m0, s38, 0x2000
	s_nop 0
	global_load_lds_dwordx4 v[198:199], off
	v_lshl_add_u64 v[198:199], s[60:61], 0, v[154:155]
	s_mov_b32 m0, s66
	s_nop 0
	global_load_lds_dwordx4 v[198:199], off
	s_mov_b32 m0, s67
	s_nop 0
	global_load_lds_dwordx4 v[216:217], off
	s_waitcnt vmcnt(8)
	s_waitcnt lgkmcnt(0)
	s_barrier
	v_mfma_f32_16x16x32_bf16 v[62:65], v[110:113], v[182:185], v[62:65]
	v_mfma_f32_16x16x32_bf16 v[58:61], v[138:141], v[182:185], v[58:61]
	v_mfma_f32_16x16x32_bf16 v[46:49], v[110:113], v[190:193], v[46:49]
	v_mfma_f32_16x16x32_bf16 v[42:45], v[138:141], v[190:193], v[42:45]
	v_mfma_f32_16x16x32_bf16 v[30:33], v[110:113], v[204:207], v[30:33]
	v_mfma_f32_16x16x32_bf16 v[26:29], v[138:141], v[204:207], v[26:29]
	v_mfma_f32_16x16x32_bf16 v[14:17], v[110:113], v[212:215], v[14:17]
	v_mfma_f32_16x16x32_bf16 v[10:13], v[138:141], v[212:215], v[10:13]
	v_mfma_f32_16x16x32_bf16 v[62:65], v[118:121], v[186:189], v[62:65]
	v_mfma_f32_16x16x32_bf16 v[58:61], v[142:145], v[186:189], v[58:61]
	v_mfma_f32_16x16x32_bf16 v[46:49], v[118:121], v[194:197], v[46:49]
	v_mfma_f32_16x16x32_bf16 v[42:45], v[142:145], v[194:197], v[42:45]
	v_mfma_f32_16x16x32_bf16 v[30:33], v[118:121], v[208:211], v[30:33]
	v_mfma_f32_16x16x32_bf16 v[26:29], v[142:145], v[208:211], v[26:29]
	v_mfma_f32_16x16x32_bf16 v[14:17], v[118:121], v[222:225], v[14:17]
	v_mfma_f32_16x16x32_bf16 v[10:13], v[142:145], v[222:225], v[10:13]
	v_mfma_f32_16x16x32_bf16 v[54:57], v[146:149], v[182:185], v[54:57]
	v_mfma_f32_16x16x32_bf16 v[50:53], v[174:177], v[182:185], v[50:53]
	v_mfma_f32_16x16x32_bf16 v[38:41], v[146:149], v[190:193], v[38:41]
	v_mfma_f32_16x16x32_bf16 v[34:37], v[174:177], v[190:193], v[34:37]
	v_mfma_f32_16x16x32_bf16 v[22:25], v[146:149], v[204:207], v[22:25]
	v_mfma_f32_16x16x32_bf16 v[18:21], v[174:177], v[204:207], v[18:21]
	v_mfma_f32_16x16x32_bf16 v[6:9], v[146:149], v[212:215], v[6:9]
	v_mfma_f32_16x16x32_bf16 v[2:5], v[174:177], v[212:215], v[2:5]
	v_mfma_f32_16x16x32_bf16 v[54:57], v[150:153], v[186:189], v[54:57]
	v_mfma_f32_16x16x32_bf16 v[50:53], v[178:181], v[186:189], v[50:53]
	v_mfma_f32_16x16x32_bf16 v[38:41], v[150:153], v[194:197], v[38:41]
	v_mfma_f32_16x16x32_bf16 v[34:37], v[178:181], v[194:197], v[34:37]
	v_mfma_f32_16x16x32_bf16 v[22:25], v[150:153], v[208:211], v[22:25]
	v_mfma_f32_16x16x32_bf16 v[18:21], v[178:181], v[208:211], v[18:21]
	v_mfma_f32_16x16x32_bf16 v[6:9], v[150:153], v[222:225], v[6:9]
	v_mfma_f32_16x16x32_bf16 v[2:5], v[178:181], v[222:225], v[2:5]
	s_barrier
	s_add_i32 s38, 0, 0x18000
	s_add_i32 s39, 0, 0x1c000
	v_add_u32_e32 v142, s38, v201
	v_add_u32_e32 v178, s39, v201
	ds_read_b128 v[110:113], v142
	ds_read_b128 v[118:121], v142 offset:1024
	ds_read_b128 v[138:141], v142 offset:2048
	ds_read_b128 v[142:145], v142 offset:3072
	ds_read_b128 v[146:149], v178
	ds_read_b128 v[150:153], v178 offset:1024
	ds_read_b128 v[174:177], v178 offset:2048
	ds_read_b128 v[178:181], v178 offset:3072
	s_add_u32 s36, s60, 0x80000
	s_addc_u32 s37, s61, 0
	s_mov_b32 m0, s68
	v_lshl_add_u64 v[226:227], s[36:37], 0, v[154:155]
	ds_read_b128 v[182:185], v203 offset:32768
	ds_read_b128 v[186:189], v203 offset:33792
	ds_read_b128 v[190:193], v203 offset:34816
	ds_read_b128 v[194:197], v203 offset:35840
	ds_read_b128 v[204:207], v203 offset:36864
	ds_read_b128 v[208:211], v203 offset:37888
	ds_read_b128 v[212:215], v203 offset:38912
	ds_read_b128 v[222:225], v203 offset:39936
	global_load_lds_dwordx4 v[226:227], off
	v_lshl_add_u64 v[226:227], s[36:37], 0, v[156:157]
	s_mov_b32 m0, s69
	s_nop 0
	global_load_lds_dwordx4 v[226:227], off
	s_waitcnt vmcnt(8)
	s_waitcnt lgkmcnt(0)
	s_barrier
	v_mfma_f32_16x16x32_bf16 v[134:137], v[110:113], v[182:185], v[134:137]
	v_mfma_f32_16x16x32_bf16 v[130:133], v[138:141], v[182:185], v[130:133]
	v_mfma_f32_16x16x32_bf16 v[114:117], v[110:113], v[190:193], v[114:117]
	v_mfma_f32_16x16x32_bf16 v[106:109], v[138:141], v[190:193], v[106:109]
	v_mfma_f32_16x16x32_bf16 v[94:97], v[110:113], v[204:207], v[94:97]
	v_mfma_f32_16x16x32_bf16 v[90:93], v[138:141], v[204:207], v[90:93]
	v_mfma_f32_16x16x32_bf16 v[78:81], v[110:113], v[212:215], v[78:81]
	v_mfma_f32_16x16x32_bf16 v[74:77], v[138:141], v[212:215], v[74:77]
	v_mfma_f32_16x16x32_bf16 v[134:137], v[118:121], v[186:189], v[134:137]
	v_mfma_f32_16x16x32_bf16 v[130:133], v[142:145], v[186:189], v[130:133]
	v_mfma_f32_16x16x32_bf16 v[114:117], v[118:121], v[194:197], v[114:117]
	v_mfma_f32_16x16x32_bf16 v[106:109], v[142:145], v[194:197], v[106:109]
	v_mfma_f32_16x16x32_bf16 v[94:97], v[118:121], v[208:211], v[94:97]
	v_mfma_f32_16x16x32_bf16 v[90:93], v[142:145], v[208:211], v[90:93]
	v_mfma_f32_16x16x32_bf16 v[78:81], v[118:121], v[222:225], v[78:81]
	v_mfma_f32_16x16x32_bf16 v[74:77], v[142:145], v[222:225], v[74:77]
	v_mfma_f32_16x16x32_bf16 v[126:129], v[146:149], v[182:185], v[126:129]
	v_mfma_f32_16x16x32_bf16 v[122:125], v[174:177], v[182:185], v[122:125]
	v_mfma_f32_16x16x32_bf16 v[102:105], v[146:149], v[190:193], v[102:105]
	v_mfma_f32_16x16x32_bf16 v[98:101], v[174:177], v[190:193], v[98:101]
	v_mfma_f32_16x16x32_bf16 v[86:89], v[146:149], v[204:207], v[86:89]
	v_mfma_f32_16x16x32_bf16 v[82:85], v[174:177], v[204:207], v[82:85]
	v_mfma_f32_16x16x32_bf16 v[70:73], v[146:149], v[212:215], v[70:73]
	v_mfma_f32_16x16x32_bf16 v[66:69], v[174:177], v[212:215], v[66:69]
	v_mfma_f32_16x16x32_bf16 v[126:129], v[150:153], v[186:189], v[126:129]
	v_mfma_f32_16x16x32_bf16 v[122:125], v[178:181], v[186:189], v[122:125]
	v_mfma_f32_16x16x32_bf16 v[102:105], v[150:153], v[194:197], v[102:105]
	v_mfma_f32_16x16x32_bf16 v[98:101], v[178:181], v[194:197], v[98:101]
	v_mfma_f32_16x16x32_bf16 v[86:89], v[150:153], v[208:211], v[86:89]
	v_mfma_f32_16x16x32_bf16 v[82:85], v[178:181], v[208:211], v[82:85]
	v_mfma_f32_16x16x32_bf16 v[70:73], v[150:153], v[222:225], v[70:73]
	v_mfma_f32_16x16x32_bf16 v[66:69], v[178:181], v[222:225], v[66:69]
	s_barrier
	s_add_i32 s36, s38, s27
	v_lshl_add_u64 v[168:169], v[168:169], 0, s[44:45]
	s_mov_b32 m0, s36
	ds_read_b128 v[182:185], v203 offset:49152
	ds_read_b128 v[186:189], v203 offset:50176
	ds_read_b128 v[190:193], v203 offset:51200
	ds_read_b128 v[194:197], v203 offset:52224
	ds_read_b128 v[204:207], v203 offset:53248
	ds_read_b128 v[208:211], v203 offset:54272
	ds_read_b128 v[212:215], v203 offset:55296
	ds_read_b128 v[222:225], v203 offset:56320
	global_load_lds_dwordx4 v[168:169], off
	s_add_i32 m0, s36, 0x2000
	s_add_u32 s36, s58, 0x80080
	v_lshl_add_u64 v[168:169], v[170:171], 0, s[44:45]
	s_addc_u32 s37, s59, 0
	s_add_i32 s38, s39, s27
	global_load_lds_dwordx4 v[168:169], off
	v_lshl_add_u64 v[168:169], s[36:37], 0, v[162:163]
	s_mov_b32 m0, s38
	s_nop 0
	global_load_lds_dwordx4 v[168:169], off
	v_lshl_add_u64 v[168:169], s[36:37], 0, v[158:159]
	s_add_i32 m0, s38, 0x2000
	s_nop 0
	global_load_lds_dwordx4 v[168:169], off
	v_lshl_add_u64 v[168:169], v[198:199], 0, s[44:45]
	s_mov_b32 m0, s70
	s_nop 0
	global_load_lds_dwordx4 v[168:169], off
	v_lshl_add_u64 v[168:169], v[216:217], 0, s[44:45]
	s_mov_b32 m0, s71
	s_nop 0
	global_load_lds_dwordx4 v[168:169], off
	s_waitcnt vmcnt(8)
	s_waitcnt lgkmcnt(0)
	s_barrier
	v_mfma_f32_16x16x32_bf16 v[62:65], v[110:113], v[182:185], v[62:65]
	v_mfma_f32_16x16x32_bf16 v[58:61], v[138:141], v[182:185], v[58:61]
	s_add_i32 s78, s78, 2
	v_mfma_f32_16x16x32_bf16 v[46:49], v[110:113], v[190:193], v[46:49]
	s_add_u32 s25, s25, 0x100
	v_mfma_f32_16x16x32_bf16 v[42:45], v[138:141], v[190:193], v[42:45]
	s_addc_u32 s62, s62, 0
	v_mfma_f32_16x16x32_bf16 v[30:33], v[110:113], v[204:207], v[30:33]
	s_add_u32 s56, s56, 0x100
	v_mfma_f32_16x16x32_bf16 v[26:29], v[138:141], v[204:207], v[26:29]
	s_addc_u32 s57, s57, 0
	v_mfma_f32_16x16x32_bf16 v[14:17], v[110:113], v[212:215], v[14:17]
	s_cmp_gt_u32 s78, 29
	v_mfma_f32_16x16x32_bf16 v[10:13], v[138:141], v[212:215], v[10:13]
	v_mfma_f32_16x16x32_bf16 v[62:65], v[118:121], v[186:189], v[62:65]
	v_mfma_f32_16x16x32_bf16 v[58:61], v[142:145], v[186:189], v[58:61]
	v_mfma_f32_16x16x32_bf16 v[46:49], v[118:121], v[194:197], v[46:49]
	v_mfma_f32_16x16x32_bf16 v[42:45], v[142:145], v[194:197], v[42:45]
	v_mfma_f32_16x16x32_bf16 v[30:33], v[118:121], v[208:211], v[30:33]
	v_mfma_f32_16x16x32_bf16 v[26:29], v[142:145], v[208:211], v[26:29]
	v_mfma_f32_16x16x32_bf16 v[14:17], v[118:121], v[222:225], v[14:17]
	v_mfma_f32_16x16x32_bf16 v[10:13], v[142:145], v[222:225], v[10:13]
	v_mfma_f32_16x16x32_bf16 v[54:57], v[146:149], v[182:185], v[54:57]
	v_mfma_f32_16x16x32_bf16 v[50:53], v[174:177], v[182:185], v[50:53]
	v_mfma_f32_16x16x32_bf16 v[38:41], v[146:149], v[190:193], v[38:41]
	v_mfma_f32_16x16x32_bf16 v[34:37], v[174:177], v[190:193], v[34:37]
	v_mfma_f32_16x16x32_bf16 v[22:25], v[146:149], v[204:207], v[22:25]
	v_mfma_f32_16x16x32_bf16 v[18:21], v[174:177], v[204:207], v[18:21]
	v_mfma_f32_16x16x32_bf16 v[6:9], v[146:149], v[212:215], v[6:9]
	v_mfma_f32_16x16x32_bf16 v[2:5], v[174:177], v[212:215], v[2:5]
	v_mfma_f32_16x16x32_bf16 v[54:57], v[150:153], v[186:189], v[54:57]
	v_mfma_f32_16x16x32_bf16 v[50:53], v[178:181], v[186:189], v[50:53]
	v_mfma_f32_16x16x32_bf16 v[38:41], v[150:153], v[194:197], v[38:41]
	v_mfma_f32_16x16x32_bf16 v[34:37], v[178:181], v[194:197], v[34:37]
	v_mfma_f32_16x16x32_bf16 v[22:25], v[150:153], v[208:211], v[22:25]
	v_mfma_f32_16x16x32_bf16 v[18:21], v[178:181], v[208:211], v[18:21]
	v_mfma_f32_16x16x32_bf16 v[6:9], v[150:153], v[222:225], v[6:9]
	v_mfma_f32_16x16x32_bf16 v[2:5], v[178:181], v[222:225], v[2:5]
	s_barrier
	s_cbranch_scc0 .LBB0_1211
	s_and_b64 vcc, exec, s[18:19]
	s_cbranch_vccz .LBB0_1214
	s_barrier

.LBB0_1332:
	s_add_u32 s26, s24, 0xfffc0080
	s_addc_u32 s27, s25, -1
	s_add_i32 s36, 0, 0x10000
	s_cmp_eq_u32 s21, 12
	s_cselect_b32 s57, s17, s27
	s_cselect_b32 s56, s16, s26
	v_add_u32_e32 v142, s36, v161
	s_cselect_b32 s27, s19, s15
	s_cselect_b32 s26, s18, s13
	s_add_i32 s38, 0, 0x14000
	ds_read_b128 v[144:147], v142
	ds_read_b128 v[148:151], v142 offset:1024
	ds_read_b128 v[152:155], v142 offset:2048
	ds_read_b128 v[178:181], v142 offset:3072
	v_add_u32_e32 v142, s38, v161
	ds_read_b128 v[182:185], v142
	ds_read_b128 v[186:189], v142 offset:1024
	ds_read_b128 v[190:193], v142 offset:2048
	ds_read_b128 v[194:197], v142 offset:3072
	v_lshl_add_u64 v[156:157], s[24:25], 0, v[140:141]
	s_add_i32 m0, s69, 0xc000
	ds_read_b128 v[198:201], v177
	ds_read_b128 v[202:205], v177 offset:1024
	ds_read_b128 v[206:209], v177 offset:2048
	ds_read_b128 v[210:213], v177 offset:3072
	ds_read_b128 v[214:217], v177 offset:4096
	ds_read_b128 v[222:225], v177 offset:5120
	ds_read_b128 v[226:229], v177 offset:6144
	ds_read_b128 v[230:233], v177 offset:7168
	global_load_lds_dwordx4 v[156:157], off
	v_lshl_add_u64 v[156:157], s[24:25], 0, v[138:139]
	s_add_i32 m0, s69, 0xe000
	s_nop 0
	global_load_lds_dwordx4 v[156:157], off
	s_waitcnt vmcnt(8)
	s_waitcnt lgkmcnt(0)
	s_barrier
	v_mfma_i32_16x16x64_i8 v[126:129], v[144:147], v[198:201], v[126:129]
	v_mfma_i32_16x16x64_i8 v[118:121], v[152:155], v[198:201], v[118:121]
	v_mfma_i32_16x16x64_i8 v[110:113], v[144:147], v[206:209], v[110:113]
	v_mfma_i32_16x16x64_i8 v[102:105], v[152:155], v[206:209], v[102:105]
	v_mfma_i32_16x16x64_i8 v[94:97], v[144:147], v[214:217], v[94:97]
	v_mfma_i32_16x16x64_i8 v[86:89], v[152:155], v[214:217], v[86:89]
	v_mfma_i32_16x16x64_i8 v[78:81], v[144:147], v[226:229], v[78:81]
	v_mfma_i32_16x16x64_i8 v[70:73], v[152:155], v[226:229], v[70:73]
	v_mfma_i32_16x16x64_i8 v[126:129], v[148:151], v[202:205], v[126:129]
	v_mfma_i32_16x16x64_i8 v[118:121], v[178:181], v[202:205], v[118:121]
	v_mfma_i32_16x16x64_i8 v[110:113], v[148:151], v[210:213], v[110:113]
	v_mfma_i32_16x16x64_i8 v[102:105], v[178:181], v[210:213], v[102:105]
	v_mfma_i32_16x16x64_i8 v[94:97], v[148:151], v[222:225], v[94:97]
	v_mfma_i32_16x16x64_i8 v[86:89], v[178:181], v[222:225], v[86:89]
	v_mfma_i32_16x16x64_i8 v[78:81], v[148:151], v[230:233], v[78:81]
	v_mfma_i32_16x16x64_i8 v[70:73], v[178:181], v[230:233], v[70:73]
	v_mfma_i32_16x16x64_i8 v[122:125], v[182:185], v[198:201], v[122:125]
	v_mfma_i32_16x16x64_i8 v[114:117], v[190:193], v[198:201], v[114:117]
	v_mfma_i32_16x16x64_i8 v[106:109], v[182:185], v[206:209], v[106:109]
	v_mfma_i32_16x16x64_i8 v[98:101], v[190:193], v[206:209], v[98:101]
	v_mfma_i32_16x16x64_i8 v[90:93], v[182:185], v[214:217], v[90:93]
	v_mfma_i32_16x16x64_i8 v[82:85], v[190:193], v[214:217], v[82:85]
	v_mfma_i32_16x16x64_i8 v[74:77], v[182:185], v[226:229], v[74:77]
	v_mfma_i32_16x16x64_i8 v[66:69], v[190:193], v[226:229], v[66:69]
	v_mfma_i32_16x16x64_i8 v[122:125], v[186:189], v[202:205], v[122:125]
	v_mfma_i32_16x16x64_i8 v[114:117], v[194:197], v[202:205], v[114:117]
	v_mfma_i32_16x16x64_i8 v[106:109], v[186:189], v[210:213], v[106:109]
	v_mfma_i32_16x16x64_i8 v[98:101], v[194:197], v[210:213], v[98:101]
	v_mfma_i32_16x16x64_i8 v[90:93], v[186:189], v[222:225], v[90:93]
	v_mfma_i32_16x16x64_i8 v[82:85], v[194:197], v[222:225], v[82:85]
	v_mfma_i32_16x16x64_i8 v[74:77], v[186:189], v[230:233], v[74:77]
	v_mfma_i32_16x16x64_i8 v[66:69], v[194:197], v[230:233], v[66:69]
	s_barrier
	s_add_i32 s36, s36, s23
	v_lshl_add_u64 v[156:157], s[26:27], 0, v[162:163]
	s_mov_b32 m0, s36
	ds_read_b128 v[198:201], v177 offset:16384
	ds_read_b128 v[202:205], v177 offset:17408
	ds_read_b128 v[206:209], v177 offset:18432
	ds_read_b128 v[210:213], v177 offset:19456
	ds_read_b128 v[214:217], v177 offset:20480
	ds_read_b128 v[222:225], v177 offset:21504
	ds_read_b128 v[226:229], v177 offset:22528
	ds_read_b128 v[230:233], v177 offset:23552
	global_load_lds_dwordx4 v[156:157], off
	s_add_i32 m0, s36, 0x2000
	s_add_u32 s36, s26, 0x80000
	v_lshl_add_u64 v[168:169], s[26:27], 0, v[134:135]
	s_addc_u32 s37, s27, 0
	s_add_i32 s38, s38, s23
	global_load_lds_dwordx4 v[168:169], off
	v_lshl_add_u64 v[170:171], s[36:37], 0, v[162:163]
	s_mov_b32 m0, s38
	v_lshl_add_u64 v[174:175], s[56:57], 0, v[132:133]
	global_load_lds_dwordx4 v[170:171], off
	v_lshl_add_u64 v[170:171], s[36:37], 0, v[134:135]
	s_add_i32 m0, s38, 0x2000
	s_nop 0
	global_load_lds_dwordx4 v[170:171], off
	v_lshl_add_u64 v[170:171], s[56:57], 0, v[130:131]
	s_mov_b32 m0, s69
	s_nop 0
	global_load_lds_dwordx4 v[170:171], off
	s_mov_b32 m0, s70
	s_nop 0
	global_load_lds_dwordx4 v[174:175], off
	s_waitcnt vmcnt(8)
	s_waitcnt lgkmcnt(0)
	s_barrier
	v_mfma_i32_16x16x64_i8 v[62:65], v[144:147], v[198:201], v[62:65]
	v_mfma_i32_16x16x64_i8 v[54:57], v[152:155], v[198:201], v[54:57]
	v_mfma_i32_16x16x64_i8 v[46:49], v[144:147], v[206:209], v[46:49]
	v_mfma_i32_16x16x64_i8 v[38:41], v[152:155], v[206:209], v[38:41]
	v_mfma_i32_16x16x64_i8 v[30:33], v[144:147], v[214:217], v[30:33]
	v_mfma_i32_16x16x64_i8 v[22:25], v[152:155], v[214:217], v[22:25]
	v_mfma_i32_16x16x64_i8 v[14:17], v[144:147], v[226:229], v[14:17]
	v_mfma_i32_16x16x64_i8 v[6:9], v[152:155], v[226:229], v[6:9]
	v_mfma_i32_16x16x64_i8 v[62:65], v[148:151], v[202:205], v[62:65]
	v_mfma_i32_16x16x64_i8 v[54:57], v[178:181], v[202:205], v[54:57]
	v_mfma_i32_16x16x64_i8 v[46:49], v[148:151], v[210:213], v[46:49]
	v_mfma_i32_16x16x64_i8 v[38:41], v[178:181], v[210:213], v[38:41]
	v_mfma_i32_16x16x64_i8 v[30:33], v[148:151], v[222:225], v[30:33]
	v_mfma_i32_16x16x64_i8 v[22:25], v[178:181], v[222:225], v[22:25]
	v_mfma_i32_16x16x64_i8 v[14:17], v[148:151], v[230:233], v[14:17]
	v_mfma_i32_16x16x64_i8 v[6:9], v[178:181], v[230:233], v[6:9]
	v_mfma_i32_16x16x64_i8 v[58:61], v[182:185], v[198:201], v[58:61]
	v_mfma_i32_16x16x64_i8 v[50:53], v[190:193], v[198:201], v[50:53]
	v_mfma_i32_16x16x64_i8 v[42:45], v[182:185], v[206:209], v[42:45]
	v_mfma_i32_16x16x64_i8 v[34:37], v[190:193], v[206:209], v[34:37]
	v_mfma_i32_16x16x64_i8 v[26:29], v[182:185], v[214:217], v[26:29]
	v_mfma_i32_16x16x64_i8 v[18:21], v[190:193], v[214:217], v[18:21]
	v_mfma_i32_16x16x64_i8 v[10:13], v[182:185], v[226:229], v[10:13]
	v_mfma_i32_16x16x64_i8 v[2:5], v[190:193], v[226:229], v[2:5]
	v_mfma_i32_16x16x64_i8 v[58:61], v[186:189], v[202:205], v[58:61]
	v_mfma_i32_16x16x64_i8 v[50:53], v[194:197], v[202:205], v[50:53]
	v_mfma_i32_16x16x64_i8 v[42:45], v[186:189], v[210:213], v[42:45]
	v_mfma_i32_16x16x64_i8 v[34:37], v[194:197], v[210:213], v[34:37]
	v_mfma_i32_16x16x64_i8 v[26:29], v[186:189], v[222:225], v[26:29]
	v_mfma_i32_16x16x64_i8 v[18:21], v[194:197], v[222:225], v[18:21]
	v_mfma_i32_16x16x64_i8 v[10:13], v[186:189], v[230:233], v[10:13]
	v_mfma_i32_16x16x64_i8 v[2:5], v[194:197], v[230:233], v[2:5]
	s_barrier
	s_add_i32 s38, 0, 0x18000
	v_add_u32_e32 v142, s38, v161
	s_add_i32 s39, 0, 0x1c000
	ds_read_b128 v[144:147], v142
	ds_read_b128 v[148:151], v142 offset:1024
	ds_read_b128 v[152:155], v142 offset:2048
	ds_read_b128 v[178:181], v142 offset:3072
	v_add_u32_e32 v142, s39, v161
	ds_read_b128 v[182:185], v142
	ds_read_b128 v[186:189], v142 offset:1024
	ds_read_b128 v[190:193], v142 offset:2048
	ds_read_b128 v[194:197], v142 offset:3072
	s_add_u32 s36, s56, 0x40000
	s_addc_u32 s37, s57, 0
	s_mov_b32 m0, s71
	v_lshl_add_u64 v[234:235], s[36:37], 0, v[130:131]
	ds_read_b128 v[198:201], v177 offset:32768
	ds_read_b128 v[202:205], v177 offset:33792
	ds_read_b128 v[206:209], v177 offset:34816
	ds_read_b128 v[210:213], v177 offset:35840
	ds_read_b128 v[214:217], v177 offset:36864
	ds_read_b128 v[222:225], v177 offset:37888
	ds_read_b128 v[226:229], v177 offset:38912
	ds_read_b128 v[230:233], v177 offset:39936
	global_load_lds_dwordx4 v[234:235], off
	v_lshl_add_u64 v[234:235], s[36:37], 0, v[132:133]
	s_mov_b32 m0, s72
	s_nop 0
	global_load_lds_dwordx4 v[234:235], off
	s_waitcnt vmcnt(8)
	s_waitcnt lgkmcnt(0)
	s_barrier
	v_mfma_i32_16x16x64_i8 v[126:129], v[144:147], v[198:201], v[126:129]
	v_mfma_i32_16x16x64_i8 v[118:121], v[152:155], v[198:201], v[118:121]
	v_mfma_i32_16x16x64_i8 v[110:113], v[144:147], v[206:209], v[110:113]
	v_mfma_i32_16x16x64_i8 v[102:105], v[152:155], v[206:209], v[102:105]
	v_mfma_i32_16x16x64_i8 v[94:97], v[144:147], v[214:217], v[94:97]
	v_mfma_i32_16x16x64_i8 v[86:89], v[152:155], v[214:217], v[86:89]
	v_mfma_i32_16x16x64_i8 v[78:81], v[144:147], v[226:229], v[78:81]
	v_mfma_i32_16x16x64_i8 v[70:73], v[152:155], v[226:229], v[70:73]
	v_mfma_i32_16x16x64_i8 v[126:129], v[148:151], v[202:205], v[126:129]
	v_mfma_i32_16x16x64_i8 v[118:121], v[178:181], v[202:205], v[118:121]
	v_mfma_i32_16x16x64_i8 v[110:113], v[148:151], v[210:213], v[110:113]
	v_mfma_i32_16x16x64_i8 v[102:105], v[178:181], v[210:213], v[102:105]
	v_mfma_i32_16x16x64_i8 v[94:97], v[148:151], v[222:225], v[94:97]
	v_mfma_i32_16x16x64_i8 v[86:89], v[178:181], v[222:225], v[86:89]
	v_mfma_i32_16x16x64_i8 v[78:81], v[148:151], v[230:233], v[78:81]
	v_mfma_i32_16x16x64_i8 v[70:73], v[178:181], v[230:233], v[70:73]
	v_mfma_i32_16x16x64_i8 v[122:125], v[182:185], v[198:201], v[122:125]
	v_mfma_i32_16x16x64_i8 v[114:117], v[190:193], v[198:201], v[114:117]
	v_mfma_i32_16x16x64_i8 v[106:109], v[182:185], v[206:209], v[106:109]
	v_mfma_i32_16x16x64_i8 v[98:101], v[190:193], v[206:209], v[98:101]
	v_mfma_i32_16x16x64_i8 v[90:93], v[182:185], v[214:217], v[90:93]
	v_mfma_i32_16x16x64_i8 v[82:85], v[190:193], v[214:217], v[82:85]
	v_mfma_i32_16x16x64_i8 v[74:77], v[182:185], v[226:229], v[74:77]
	v_mfma_i32_16x16x64_i8 v[66:69], v[190:193], v[226:229], v[66:69]
	v_mfma_i32_16x16x64_i8 v[122:125], v[186:189], v[202:205], v[122:125]
	v_mfma_i32_16x16x64_i8 v[114:117], v[194:197], v[202:205], v[114:117]
	v_mfma_i32_16x16x64_i8 v[106:109], v[186:189], v[210:213], v[106:109]
	v_mfma_i32_16x16x64_i8 v[98:101], v[194:197], v[210:213], v[98:101]
	v_mfma_i32_16x16x64_i8 v[90:93], v[186:189], v[222:225], v[90:93]
	v_mfma_i32_16x16x64_i8 v[82:85], v[194:197], v[222:225], v[82:85]
	v_mfma_i32_16x16x64_i8 v[74:77], v[186:189], v[230:233], v[74:77]
	v_mfma_i32_16x16x64_i8 v[66:69], v[194:197], v[230:233], v[66:69]
	s_barrier
	s_add_i32 s36, s38, s23
	v_lshl_add_u64 v[156:157], v[156:157], 0, s[44:45]
	s_mov_b32 m0, s36
	ds_read_b128 v[198:201], v177 offset:49152
	ds_read_b128 v[202:205], v177 offset:50176
	ds_read_b128 v[206:209], v177 offset:51200
	ds_read_b128 v[210:213], v177 offset:52224
	ds_read_b128 v[214:217], v177 offset:53248
	ds_read_b128 v[222:225], v177 offset:54272
	ds_read_b128 v[226:229], v177 offset:55296
	ds_read_b128 v[230:233], v177 offset:56320
	global_load_lds_dwordx4 v[156:157], off
	s_add_i32 m0, s36, 0x2000
	s_add_u32 s26, s26, 0x80080
	v_lshl_add_u64 v[156:157], v[168:169], 0, s[44:45]
	s_addc_u32 s27, s27, 0
	s_add_i32 s36, s39, s23
	global_load_lds_dwordx4 v[156:157], off
	v_lshl_add_u64 v[156:157], s[26:27], 0, v[162:163]
	s_mov_b32 m0, s36
	s_nop 0
	global_load_lds_dwordx4 v[156:157], off
	v_lshl_add_u64 v[156:157], s[26:27], 0, v[134:135]
	s_add_i32 m0, s36, 0x2000
	s_nop 0
	global_load_lds_dwordx4 v[156:157], off
	v_lshl_add_u64 v[156:157], v[170:171], 0, s[44:45]
	s_mov_b32 m0, s73
	s_nop 0
	global_load_lds_dwordx4 v[156:157], off
	v_lshl_add_u64 v[156:157], v[174:175], 0, s[44:45]
	s_mov_b32 m0, s74
	s_nop 0
	global_load_lds_dwordx4 v[156:157], off
	s_waitcnt vmcnt(8)
	s_waitcnt lgkmcnt(0)
	s_barrier
	v_mfma_i32_16x16x64_i8 v[62:65], v[144:147], v[198:201], v[62:65]
	v_mfma_i32_16x16x64_i8 v[54:57], v[152:155], v[198:201], v[54:57]
	s_add_i32 s21, s21, 2
	v_mfma_i32_16x16x64_i8 v[46:49], v[144:147], v[206:209], v[46:49]
	s_add_u32 s13, s13, 0x100
	v_mfma_i32_16x16x64_i8 v[38:41], v[152:155], v[206:209], v[38:41]
	s_addc_u32 s15, s15, 0
	v_mfma_i32_16x16x64_i8 v[30:33], v[144:147], v[214:217], v[30:33]
	s_add_u32 s24, s24, 0x100
	v_mfma_i32_16x16x64_i8 v[22:25], v[152:155], v[214:217], v[22:25]
	s_addc_u32 s25, s25, 0
	v_mfma_i32_16x16x64_i8 v[14:17], v[144:147], v[226:229], v[14:17]
	s_cmp_gt_u32 s21, 13
	v_mfma_i32_16x16x64_i8 v[6:9], v[152:155], v[226:229], v[6:9]
	v_mfma_i32_16x16x64_i8 v[62:65], v[148:151], v[202:205], v[62:65]
	v_mfma_i32_16x16x64_i8 v[54:57], v[178:181], v[202:205], v[54:57]
	v_mfma_i32_16x16x64_i8 v[46:49], v[148:151], v[210:213], v[46:49]
	v_mfma_i32_16x16x64_i8 v[38:41], v[178:181], v[210:213], v[38:41]
	v_mfma_i32_16x16x64_i8 v[30:33], v[148:151], v[222:225], v[30:33]
	v_mfma_i32_16x16x64_i8 v[22:25], v[178:181], v[222:225], v[22:25]
	v_mfma_i32_16x16x64_i8 v[14:17], v[148:151], v[230:233], v[14:17]
	v_mfma_i32_16x16x64_i8 v[6:9], v[178:181], v[230:233], v[6:9]
	v_mfma_i32_16x16x64_i8 v[58:61], v[182:185], v[198:201], v[58:61]
	v_mfma_i32_16x16x64_i8 v[50:53], v[190:193], v[198:201], v[50:53]
	v_mfma_i32_16x16x64_i8 v[42:45], v[182:185], v[206:209], v[42:45]
	v_mfma_i32_16x16x64_i8 v[34:37], v[190:193], v[206:209], v[34:37]
	v_mfma_i32_16x16x64_i8 v[26:29], v[182:185], v[214:217], v[26:29]
	v_mfma_i32_16x16x64_i8 v[18:21], v[190:193], v[214:217], v[18:21]
	v_mfma_i32_16x16x64_i8 v[10:13], v[182:185], v[226:229], v[10:13]
	v_mfma_i32_16x16x64_i8 v[2:5], v[190:193], v[226:229], v[2:5]
	v_mfma_i32_16x16x64_i8 v[58:61], v[186:189], v[202:205], v[58:61]
	v_mfma_i32_16x16x64_i8 v[50:53], v[194:197], v[202:205], v[50:53]
	v_mfma_i32_16x16x64_i8 v[42:45], v[186:189], v[210:213], v[42:45]
	v_mfma_i32_16x16x64_i8 v[34:37], v[194:197], v[210:213], v[34:37]
	v_mfma_i32_16x16x64_i8 v[26:29], v[186:189], v[222:225], v[26:29]
	v_mfma_i32_16x16x64_i8 v[18:21], v[194:197], v[222:225], v[18:21]
	v_mfma_i32_16x16x64_i8 v[10:13], v[186:189], v[230:233], v[10:13]
	v_mfma_i32_16x16x64_i8 v[2:5], v[194:197], v[230:233], v[2:5]
	s_barrier
	s_cbranch_scc0 .LBB0_1332
	s_and_b64 vcc, exec, s[10:11]
	s_cbranch_vccz .LBB0_1335
	s_barrier

.LBB0_1446:
	s_add_u32 s8, s26, 0x4000
	s_addc_u32 s9, s27, 0
	s_cmpk_eq_i32 s84, 0x54
	s_cselect_b32 s60, s22, s8
	s_cselect_b32 s61, s23, s9
	s_cselect_b32 s58, s24, s82
	s_cselect_b32 s59, s25, s83
	s_add_u32 s56, s60, 0x8000
	s_addc_u32 s57, s61, 0
	s_add_i32 s8, 0, 0x10000
	s_add_i32 s36, 0, 0x14000
	v_add_u32_e32 v142, s8, v201
	v_add_u32_e32 v168, s36, v201
	ds_read_b128 v[110:113], v142
	ds_read_b128 v[118:121], v142 offset:1024
	ds_read_b128 v[138:141], v142 offset:2048
	ds_read_b128 v[142:145], v142 offset:3072
	ds_read_b128 v[146:149], v168
	ds_read_b128 v[150:153], v168 offset:1024
	ds_read_b128 v[174:177], v168 offset:2048
	ds_read_b128 v[178:181], v168 offset:3072
	v_lshl_add_u64 v[168:169], s[26:27], 0, v[172:173]
	s_add_i32 m0, s65, 0xc000
	ds_read_b128 v[182:185], v203
	ds_read_b128 v[186:189], v203 offset:1024
	ds_read_b128 v[190:193], v203 offset:2048
	ds_read_b128 v[194:197], v203 offset:3072
	ds_read_b128 v[204:207], v203 offset:4096
	ds_read_b128 v[208:211], v203 offset:5120
	ds_read_b128 v[212:215], v203 offset:6144
	ds_read_b128 v[222:225], v203 offset:7168
	global_load_lds_dwordx4 v[168:169], off
	v_lshl_add_u64 v[168:169], s[26:27], 0, v[160:161]
	s_add_i32 m0, s65, 0xe000
	s_nop 0
	global_load_lds_dwordx4 v[168:169], off
	s_waitcnt vmcnt(8)
	s_waitcnt lgkmcnt(0)
	s_barrier
	v_mfma_f32_16x16x32_bf16 v[134:137], v[110:113], v[182:185], v[134:137]
	v_mfma_f32_16x16x32_bf16 v[130:133], v[138:141], v[182:185], v[130:133]
	v_mfma_f32_16x16x32_bf16 v[114:117], v[110:113], v[190:193], v[114:117]
	v_mfma_f32_16x16x32_bf16 v[106:109], v[138:141], v[190:193], v[106:109]
	v_mfma_f32_16x16x32_bf16 v[94:97], v[110:113], v[204:207], v[94:97]
	v_mfma_f32_16x16x32_bf16 v[90:93], v[138:141], v[204:207], v[90:93]
	v_mfma_f32_16x16x32_bf16 v[78:81], v[110:113], v[212:215], v[78:81]
	v_mfma_f32_16x16x32_bf16 v[74:77], v[138:141], v[212:215], v[74:77]
	v_mfma_f32_16x16x32_bf16 v[134:137], v[118:121], v[186:189], v[134:137]
	v_mfma_f32_16x16x32_bf16 v[130:133], v[142:145], v[186:189], v[130:133]
	v_mfma_f32_16x16x32_bf16 v[114:117], v[118:121], v[194:197], v[114:117]
	v_mfma_f32_16x16x32_bf16 v[106:109], v[142:145], v[194:197], v[106:109]
	v_mfma_f32_16x16x32_bf16 v[94:97], v[118:121], v[208:211], v[94:97]
	v_mfma_f32_16x16x32_bf16 v[90:93], v[142:145], v[208:211], v[90:93]
	v_mfma_f32_16x16x32_bf16 v[78:81], v[118:121], v[222:225], v[78:81]
	v_mfma_f32_16x16x32_bf16 v[74:77], v[142:145], v[222:225], v[74:77]
	v_mfma_f32_16x16x32_bf16 v[126:129], v[146:149], v[182:185], v[126:129]
	v_mfma_f32_16x16x32_bf16 v[122:125], v[174:177], v[182:185], v[122:125]
	v_mfma_f32_16x16x32_bf16 v[102:105], v[146:149], v[190:193], v[102:105]
	v_mfma_f32_16x16x32_bf16 v[98:101], v[174:177], v[190:193], v[98:101]
	v_mfma_f32_16x16x32_bf16 v[86:89], v[146:149], v[204:207], v[86:89]
	v_mfma_f32_16x16x32_bf16 v[82:85], v[174:177], v[204:207], v[82:85]
	v_mfma_f32_16x16x32_bf16 v[70:73], v[146:149], v[212:215], v[70:73]
	v_mfma_f32_16x16x32_bf16 v[66:69], v[174:177], v[212:215], v[66:69]
	v_mfma_f32_16x16x32_bf16 v[126:129], v[150:153], v[186:189], v[126:129]
	v_mfma_f32_16x16x32_bf16 v[122:125], v[178:181], v[186:189], v[122:125]
	v_mfma_f32_16x16x32_bf16 v[102:105], v[150:153], v[194:197], v[102:105]
	v_mfma_f32_16x16x32_bf16 v[98:101], v[178:181], v[194:197], v[98:101]
	v_mfma_f32_16x16x32_bf16 v[86:89], v[150:153], v[208:211], v[86:89]
	v_mfma_f32_16x16x32_bf16 v[82:85], v[178:181], v[208:211], v[82:85]
	v_mfma_f32_16x16x32_bf16 v[70:73], v[150:153], v[222:225], v[70:73]
	v_mfma_f32_16x16x32_bf16 v[66:69], v[178:181], v[222:225], v[66:69]
	s_barrier
	s_add_i32 s8, s8, s64
	v_lshl_add_u64 v[168:169], s[58:59], 0, v[162:163]
	s_mov_b32 m0, s8
	ds_read_b128 v[182:185], v203 offset:16384
	ds_read_b128 v[186:189], v203 offset:17408
	ds_read_b128 v[190:193], v203 offset:18432
	ds_read_b128 v[194:197], v203 offset:19456
	ds_read_b128 v[204:207], v203 offset:20480
	ds_read_b128 v[208:211], v203 offset:21504
	ds_read_b128 v[212:215], v203 offset:22528
	ds_read_b128 v[222:225], v203 offset:23552
	global_load_lds_dwordx4 v[168:169], off
	s_add_i32 m0, s8, 0x2000
	s_add_u32 s8, s58, 0x160000
	v_lshl_add_u64 v[170:171], s[58:59], 0, v[158:159]
	s_addc_u32 s9, s59, 0
	s_add_i32 s36, s36, s64
	global_load_lds_dwordx4 v[170:171], off
	v_lshl_add_u64 v[198:199], s[8:9], 0, v[162:163]
	s_mov_b32 m0, s36
	s_nop 0
	global_load_lds_dwordx4 v[198:199], off
	v_lshl_add_u64 v[198:199], s[8:9], 0, v[158:159]
	s_add_i32 m0, s36, 0x2000
	s_nop 0
	global_load_lds_dwordx4 v[198:199], off
	v_lshl_add_u64 v[198:199], s[60:61], 0, v[154:155]
	s_mov_b32 m0, s65
	s_nop 0
	global_load_lds_dwordx4 v[198:199], off
	v_lshl_add_u64 v[198:199], s[60:61], 0, v[156:157]
	s_mov_b32 m0, s66
	s_nop 0
	global_load_lds_dwordx4 v[198:199], off
	s_waitcnt vmcnt(8)
	s_waitcnt lgkmcnt(0)
	s_barrier
	v_mfma_f32_16x16x32_bf16 v[62:65], v[110:113], v[182:185], v[62:65]
	v_mfma_f32_16x16x32_bf16 v[58:61], v[138:141], v[182:185], v[58:61]
	v_mfma_f32_16x16x32_bf16 v[46:49], v[110:113], v[190:193], v[46:49]
	v_mfma_f32_16x16x32_bf16 v[42:45], v[138:141], v[190:193], v[42:45]
	v_mfma_f32_16x16x32_bf16 v[30:33], v[110:113], v[204:207], v[30:33]
	v_mfma_f32_16x16x32_bf16 v[26:29], v[138:141], v[204:207], v[26:29]
	v_mfma_f32_16x16x32_bf16 v[14:17], v[110:113], v[212:215], v[14:17]
	v_mfma_f32_16x16x32_bf16 v[10:13], v[138:141], v[212:215], v[10:13]
	v_mfma_f32_16x16x32_bf16 v[62:65], v[118:121], v[186:189], v[62:65]
	v_mfma_f32_16x16x32_bf16 v[58:61], v[142:145], v[186:189], v[58:61]
	v_mfma_f32_16x16x32_bf16 v[46:49], v[118:121], v[194:197], v[46:49]
	v_mfma_f32_16x16x32_bf16 v[42:45], v[142:145], v[194:197], v[42:45]
	v_mfma_f32_16x16x32_bf16 v[30:33], v[118:121], v[208:211], v[30:33]
	v_mfma_f32_16x16x32_bf16 v[26:29], v[142:145], v[208:211], v[26:29]
	v_mfma_f32_16x16x32_bf16 v[14:17], v[118:121], v[222:225], v[14:17]
	v_mfma_f32_16x16x32_bf16 v[10:13], v[142:145], v[222:225], v[10:13]
	v_mfma_f32_16x16x32_bf16 v[54:57], v[146:149], v[182:185], v[54:57]
	v_mfma_f32_16x16x32_bf16 v[50:53], v[174:177], v[182:185], v[50:53]
	v_mfma_f32_16x16x32_bf16 v[38:41], v[146:149], v[190:193], v[38:41]
	v_mfma_f32_16x16x32_bf16 v[34:37], v[174:177], v[190:193], v[34:37]
	v_mfma_f32_16x16x32_bf16 v[22:25], v[146:149], v[204:207], v[22:25]
	v_mfma_f32_16x16x32_bf16 v[18:21], v[174:177], v[204:207], v[18:21]
	v_mfma_f32_16x16x32_bf16 v[6:9], v[146:149], v[212:215], v[6:9]
	v_mfma_f32_16x16x32_bf16 v[2:5], v[174:177], v[212:215], v[2:5]
	v_mfma_f32_16x16x32_bf16 v[54:57], v[150:153], v[186:189], v[54:57]
	v_mfma_f32_16x16x32_bf16 v[50:53], v[178:181], v[186:189], v[50:53]
	v_mfma_f32_16x16x32_bf16 v[38:41], v[150:153], v[194:197], v[38:41]
	v_mfma_f32_16x16x32_bf16 v[34:37], v[178:181], v[194:197], v[34:37]
	v_mfma_f32_16x16x32_bf16 v[22:25], v[150:153], v[208:211], v[22:25]
	v_mfma_f32_16x16x32_bf16 v[18:21], v[178:181], v[208:211], v[18:21]
	v_mfma_f32_16x16x32_bf16 v[6:9], v[150:153], v[222:225], v[6:9]
	v_mfma_f32_16x16x32_bf16 v[2:5], v[178:181], v[222:225], v[2:5]
	s_barrier
	s_add_i32 s36, 0, 0x18000
	s_add_i32 s37, 0, 0x1c000
	v_add_u32_e32 v142, s36, v201
	v_add_u32_e32 v178, s37, v201
	ds_read_b128 v[110:113], v142
	ds_read_b128 v[118:121], v142 offset:1024
	ds_read_b128 v[138:141], v142 offset:2048
	ds_read_b128 v[142:145], v142 offset:3072
	ds_read_b128 v[146:149], v178
	ds_read_b128 v[150:153], v178 offset:1024
	ds_read_b128 v[174:177], v178 offset:2048
	ds_read_b128 v[178:181], v178 offset:3072
	s_add_u32 s8, s60, 0x4000
	s_addc_u32 s9, s61, 0
	s_mov_b32 m0, s67
	v_lshl_add_u64 v[198:199], s[8:9], 0, v[154:155]
	ds_read_b128 v[182:185], v203 offset:32768
	ds_read_b128 v[186:189], v203 offset:33792
	ds_read_b128 v[190:193], v203 offset:34816
	ds_read_b128 v[194:197], v203 offset:35840
	ds_read_b128 v[204:207], v203 offset:36864
	ds_read_b128 v[208:211], v203 offset:37888
	ds_read_b128 v[212:215], v203 offset:38912
	ds_read_b128 v[222:225], v203 offset:39936
	global_load_lds_dwordx4 v[198:199], off
	v_lshl_add_u64 v[198:199], s[8:9], 0, v[156:157]
	s_mov_b32 m0, s68
	s_nop 0
	global_load_lds_dwordx4 v[198:199], off
	s_waitcnt vmcnt(8)
	s_waitcnt lgkmcnt(0)
	s_barrier
	v_mfma_f32_16x16x32_bf16 v[134:137], v[110:113], v[182:185], v[134:137]
	v_mfma_f32_16x16x32_bf16 v[130:133], v[138:141], v[182:185], v[130:133]
	v_mfma_f32_16x16x32_bf16 v[114:117], v[110:113], v[190:193], v[114:117]
	v_mfma_f32_16x16x32_bf16 v[106:109], v[138:141], v[190:193], v[106:109]
	v_mfma_f32_16x16x32_bf16 v[94:97], v[110:113], v[204:207], v[94:97]
	v_mfma_f32_16x16x32_bf16 v[90:93], v[138:141], v[204:207], v[90:93]
	v_mfma_f32_16x16x32_bf16 v[78:81], v[110:113], v[212:215], v[78:81]
	v_mfma_f32_16x16x32_bf16 v[74:77], v[138:141], v[212:215], v[74:77]
	v_mfma_f32_16x16x32_bf16 v[134:137], v[118:121], v[186:189], v[134:137]
	v_mfma_f32_16x16x32_bf16 v[130:133], v[142:145], v[186:189], v[130:133]
	v_mfma_f32_16x16x32_bf16 v[114:117], v[118:121], v[194:197], v[114:117]
	v_mfma_f32_16x16x32_bf16 v[106:109], v[142:145], v[194:197], v[106:109]
	v_mfma_f32_16x16x32_bf16 v[94:97], v[118:121], v[208:211], v[94:97]
	v_mfma_f32_16x16x32_bf16 v[90:93], v[142:145], v[208:211], v[90:93]
	v_mfma_f32_16x16x32_bf16 v[78:81], v[118:121], v[222:225], v[78:81]
	v_mfma_f32_16x16x32_bf16 v[74:77], v[142:145], v[222:225], v[74:77]
	v_mfma_f32_16x16x32_bf16 v[126:129], v[146:149], v[182:185], v[126:129]
	v_mfma_f32_16x16x32_bf16 v[122:125], v[174:177], v[182:185], v[122:125]
	v_mfma_f32_16x16x32_bf16 v[102:105], v[146:149], v[190:193], v[102:105]
	v_mfma_f32_16x16x32_bf16 v[98:101], v[174:177], v[190:193], v[98:101]
	v_mfma_f32_16x16x32_bf16 v[86:89], v[146:149], v[204:207], v[86:89]
	v_mfma_f32_16x16x32_bf16 v[82:85], v[174:177], v[204:207], v[82:85]
	v_mfma_f32_16x16x32_bf16 v[70:73], v[146:149], v[212:215], v[70:73]
	v_mfma_f32_16x16x32_bf16 v[66:69], v[174:177], v[212:215], v[66:69]
	v_mfma_f32_16x16x32_bf16 v[126:129], v[150:153], v[186:189], v[126:129]
	v_mfma_f32_16x16x32_bf16 v[122:125], v[178:181], v[186:189], v[122:125]
	v_mfma_f32_16x16x32_bf16 v[102:105], v[150:153], v[194:197], v[102:105]
	v_mfma_f32_16x16x32_bf16 v[98:101], v[178:181], v[194:197], v[98:101]
	v_mfma_f32_16x16x32_bf16 v[86:89], v[150:153], v[208:211], v[86:89]
	v_mfma_f32_16x16x32_bf16 v[82:85], v[178:181], v[208:211], v[82:85]
	v_mfma_f32_16x16x32_bf16 v[70:73], v[150:153], v[222:225], v[70:73]
	v_mfma_f32_16x16x32_bf16 v[66:69], v[178:181], v[222:225], v[66:69]
	s_barrier
	s_add_i32 s8, s36, s64
	v_lshl_add_u64 v[168:169], v[168:169], 0, s[44:45]
	s_mov_b32 m0, s8
	ds_read_b128 v[182:185], v203 offset:49152
	ds_read_b128 v[186:189], v203 offset:50176
	ds_read_b128 v[190:193], v203 offset:51200
	ds_read_b128 v[194:197], v203 offset:52224
	ds_read_b128 v[204:207], v203 offset:53248
	ds_read_b128 v[208:211], v203 offset:54272
	ds_read_b128 v[212:215], v203 offset:55296
	ds_read_b128 v[222:225], v203 offset:56320
	global_load_lds_dwordx4 v[168:169], off
	s_add_i32 m0, s8, 0x2000
	s_add_u32 s8, s58, 0x160080
	v_lshl_add_u64 v[168:169], v[170:171], 0, s[44:45]
	s_addc_u32 s9, s59, 0
	s_add_i32 s36, s37, s64
	global_load_lds_dwordx4 v[168:169], off
	v_lshl_add_u64 v[168:169], s[8:9], 0, v[162:163]
	s_mov_b32 m0, s36
	s_nop 0
	global_load_lds_dwordx4 v[168:169], off
	v_lshl_add_u64 v[168:169], s[8:9], 0, v[158:159]
	s_add_i32 m0, s36, 0x2000
	s_nop 0
	global_load_lds_dwordx4 v[168:169], off
	v_lshl_add_u64 v[168:169], s[56:57], 0, v[154:155]
	s_mov_b32 m0, s69
	s_nop 0
	global_load_lds_dwordx4 v[168:169], off
	v_lshl_add_u64 v[168:169], s[56:57], 0, v[156:157]
	s_mov_b32 m0, s70
	s_nop 0
	global_load_lds_dwordx4 v[168:169], off
	s_waitcnt vmcnt(8)
	s_waitcnt lgkmcnt(0)
	s_barrier
	v_mfma_f32_16x16x32_bf16 v[62:65], v[110:113], v[182:185], v[62:65]
	v_mfma_f32_16x16x32_bf16 v[58:61], v[138:141], v[182:185], v[58:61]
	s_add_i32 s84, s84, 2
	v_mfma_f32_16x16x32_bf16 v[46:49], v[110:113], v[190:193], v[46:49]
	s_add_u32 s26, s26, 0x10000
	v_mfma_f32_16x16x32_bf16 v[42:45], v[138:141], v[190:193], v[42:45]
	s_addc_u32 s27, s27, 0
	v_mfma_f32_16x16x32_bf16 v[30:33], v[110:113], v[204:207], v[30:33]
	s_add_u32 s82, s82, 0x100
	v_mfma_f32_16x16x32_bf16 v[26:29], v[138:141], v[204:207], v[26:29]
	s_addc_u32 s83, s83, 0
	v_mfma_f32_16x16x32_bf16 v[14:17], v[110:113], v[212:215], v[14:17]
	s_cmpk_gt_u32 s84, 0x55
	v_mfma_f32_16x16x32_bf16 v[10:13], v[138:141], v[212:215], v[10:13]
	v_mfma_f32_16x16x32_bf16 v[62:65], v[118:121], v[186:189], v[62:65]
	v_mfma_f32_16x16x32_bf16 v[58:61], v[142:145], v[186:189], v[58:61]
	v_mfma_f32_16x16x32_bf16 v[46:49], v[118:121], v[194:197], v[46:49]
	v_mfma_f32_16x16x32_bf16 v[42:45], v[142:145], v[194:197], v[42:45]
	v_mfma_f32_16x16x32_bf16 v[30:33], v[118:121], v[208:211], v[30:33]
	v_mfma_f32_16x16x32_bf16 v[26:29], v[142:145], v[208:211], v[26:29]
	v_mfma_f32_16x16x32_bf16 v[14:17], v[118:121], v[222:225], v[14:17]
	v_mfma_f32_16x16x32_bf16 v[10:13], v[142:145], v[222:225], v[10:13]
	v_mfma_f32_16x16x32_bf16 v[54:57], v[146:149], v[182:185], v[54:57]
	v_mfma_f32_16x16x32_bf16 v[50:53], v[174:177], v[182:185], v[50:53]
	v_mfma_f32_16x16x32_bf16 v[38:41], v[146:149], v[190:193], v[38:41]
	v_mfma_f32_16x16x32_bf16 v[34:37], v[174:177], v[190:193], v[34:37]
	v_mfma_f32_16x16x32_bf16 v[22:25], v[146:149], v[204:207], v[22:25]
	v_mfma_f32_16x16x32_bf16 v[18:21], v[174:177], v[204:207], v[18:21]
	v_mfma_f32_16x16x32_bf16 v[6:9], v[146:149], v[212:215], v[6:9]
	v_mfma_f32_16x16x32_bf16 v[2:5], v[174:177], v[212:215], v[2:5]
	v_mfma_f32_16x16x32_bf16 v[54:57], v[150:153], v[186:189], v[54:57]
	v_mfma_f32_16x16x32_bf16 v[50:53], v[178:181], v[186:189], v[50:53]
	v_mfma_f32_16x16x32_bf16 v[38:41], v[150:153], v[194:197], v[38:41]
	v_mfma_f32_16x16x32_bf16 v[34:37], v[178:181], v[194:197], v[34:37]
	v_mfma_f32_16x16x32_bf16 v[22:25], v[150:153], v[208:211], v[22:25]
	v_mfma_f32_16x16x32_bf16 v[18:21], v[178:181], v[208:211], v[18:21]
	v_mfma_f32_16x16x32_bf16 v[6:9], v[150:153], v[222:225], v[6:9]
	v_mfma_f32_16x16x32_bf16 v[2:5], v[178:181], v[222:225], v[2:5]
	s_barrier
	s_cbranch_scc0 .LBB0_1446
	s_and_b64 vcc, exec, s[20:21]
	s_cbranch_vccz .LBB0_1449
	s_barrier

.LBB0_1615:
	s_add_u32 s31, s64, 0xfffc0080
	s_addc_u32 s36, s65, -1
	s_add_i32 s37, 0, 0x10000
	s_cmp_eq_u32 s27, 12
	s_cselect_b32 vcc_hi, s57, s36
	s_cselect_b32 vcc_lo, s56, s31
	s_cselect_b32 s67, s59, s26
	s_cselect_b32 s66, s58, s25
	s_add_i32 s31, 0, 0x14000
	v_add_u32_e32 v142, s37, v201
	v_add_u32_e32 v158, s31, v201
	ds_read_b128 v[66:69], v142
	ds_read_b128 v[70:73], v142 offset:1024
	ds_read_b128 v[138:141], v142 offset:2048
	ds_read_b128 v[142:145], v142 offset:3072
	ds_read_b128 v[146:149], v158
	ds_read_b128 v[150:153], v158 offset:1024
	ds_read_b128 v[154:157], v158 offset:2048
	ds_read_b128 v[158:161], v158 offset:3072
	v_lshl_add_u64 v[168:169], s[64:65], 0, v[180:181]
	s_add_i32 m0, s63, 0xc000
	ds_read_b128 v[182:185], v222
	ds_read_b128 v[186:189], v222 offset:1024
	ds_read_b128 v[190:193], v222 offset:2048
	ds_read_b128 v[202:205], v222 offset:3072
	ds_read_b128 v[206:209], v222 offset:4096
	ds_read_b128 v[210:213], v222 offset:5120
	ds_read_b128 v[224:227], v222 offset:6144
	ds_read_b128 v[228:231], v222 offset:7168
	global_load_lds_dwordx4 v[168:169], off
	v_lshl_add_u64 v[168:169], s[64:65], 0, v[178:179]
	s_add_i32 m0, s63, 0xe000
	s_nop 0
	global_load_lds_dwordx4 v[168:169], off
	s_waitcnt vmcnt(8)
	s_waitcnt lgkmcnt(0)
	s_barrier
	v_mfma_i32_16x16x64_i8 v[134:137], v[66:69], v[182:185], v[134:137]
	v_mfma_i32_16x16x64_i8 v[130:133], v[138:141], v[182:185], v[130:133]
	v_mfma_i32_16x16x64_i8 v[126:129], v[66:69], v[190:193], v[126:129]
	v_mfma_i32_16x16x64_i8 v[122:125], v[138:141], v[190:193], v[122:125]
	v_mfma_i32_16x16x64_i8 v[118:121], v[66:69], v[206:209], v[118:121]
	v_mfma_i32_16x16x64_i8 v[114:117], v[138:141], v[206:209], v[114:117]
	v_mfma_i32_16x16x64_i8 v[78:81], v[66:69], v[224:227], v[78:81]
	v_mfma_i32_16x16x64_i8 v[74:77], v[138:141], v[224:227], v[74:77]
	v_mfma_i32_16x16x64_i8 v[134:137], v[70:73], v[186:189], v[134:137]
	v_mfma_i32_16x16x64_i8 v[130:133], v[142:145], v[186:189], v[130:133]
	v_mfma_i32_16x16x64_i8 v[126:129], v[70:73], v[202:205], v[126:129]
	v_mfma_i32_16x16x64_i8 v[122:125], v[142:145], v[202:205], v[122:125]
	v_mfma_i32_16x16x64_i8 v[118:121], v[70:73], v[210:213], v[118:121]
	v_mfma_i32_16x16x64_i8 v[114:117], v[142:145], v[210:213], v[114:117]
	v_mfma_i32_16x16x64_i8 v[78:81], v[70:73], v[228:231], v[78:81]
	v_mfma_i32_16x16x64_i8 v[74:77], v[142:145], v[228:231], v[74:77]
	v_mfma_i32_16x16x64_i8 v[110:113], v[146:149], v[182:185], v[110:113]
	v_mfma_i32_16x16x64_i8 v[106:109], v[154:157], v[182:185], v[106:109]
	v_mfma_i32_16x16x64_i8 v[102:105], v[146:149], v[190:193], v[102:105]
	v_mfma_i32_16x16x64_i8 v[98:101], v[154:157], v[190:193], v[98:101]
	v_mfma_i32_16x16x64_i8 v[94:97], v[146:149], v[206:209], v[94:97]
	v_mfma_i32_16x16x64_i8 v[90:93], v[154:157], v[206:209], v[90:93]
	v_mfma_i32_16x16x64_i8 v[86:89], v[146:149], v[224:227], v[86:89]
	v_mfma_i32_16x16x64_i8 v[82:85], v[154:157], v[224:227], v[82:85]
	v_mfma_i32_16x16x64_i8 v[110:113], v[150:153], v[186:189], v[110:113]
	v_mfma_i32_16x16x64_i8 v[106:109], v[158:161], v[186:189], v[106:109]
	v_mfma_i32_16x16x64_i8 v[102:105], v[150:153], v[202:205], v[102:105]
	v_mfma_i32_16x16x64_i8 v[98:101], v[158:161], v[202:205], v[98:101]
	v_mfma_i32_16x16x64_i8 v[94:97], v[150:153], v[210:213], v[94:97]
	v_mfma_i32_16x16x64_i8 v[90:93], v[158:161], v[210:213], v[90:93]
	v_mfma_i32_16x16x64_i8 v[86:89], v[150:153], v[228:231], v[86:89]
	v_mfma_i32_16x16x64_i8 v[82:85], v[158:161], v[228:231], v[82:85]
	s_barrier
	s_add_i32 s36, s37, s61
	v_lshl_add_u64 v[168:169], s[66:67], 0, v[162:163]
	s_mov_b32 m0, s36
	ds_read_b128 v[182:185], v222 offset:16384
	ds_read_b128 v[186:189], v222 offset:17408
	ds_read_b128 v[190:193], v222 offset:18432
	ds_read_b128 v[202:205], v222 offset:19456
	ds_read_b128 v[206:209], v222 offset:20480
	ds_read_b128 v[210:213], v222 offset:21504
	ds_read_b128 v[224:227], v222 offset:22528
	ds_read_b128 v[228:231], v222 offset:23552
	global_load_lds_dwordx4 v[168:169], off
	s_add_i32 m0, s36, 0x2000
	s_add_u32 s36, s66, 0x90000
	v_lshl_add_u64 v[170:171], s[66:67], 0, v[176:177]
	s_addc_u32 s37, s67, 0
	s_add_i32 s31, s31, s61
	global_load_lds_dwordx4 v[170:171], off
	v_lshl_add_u64 v[214:215], s[36:37], 0, v[162:163]
	s_mov_b32 m0, s31
	v_lshl_add_u64 v[232:233], vcc, 0, v[174:175]
	global_load_lds_dwordx4 v[214:215], off
	v_lshl_add_u64 v[214:215], s[36:37], 0, v[176:177]
	s_add_i32 m0, s31, 0x2000
	s_nop 0
	global_load_lds_dwordx4 v[214:215], off
	v_lshl_add_u64 v[214:215], vcc, 0, v[172:173]
	s_mov_b32 m0, s63
	s_nop 0
	global_load_lds_dwordx4 v[214:215], off
	s_mov_b32 m0, s78
	s_nop 0
	global_load_lds_dwordx4 v[232:233], off
	s_waitcnt vmcnt(8)
	s_waitcnt lgkmcnt(0)
	s_barrier
	v_mfma_i32_16x16x64_i8 v[62:65], v[66:69], v[182:185], v[62:65]
	v_mfma_i32_16x16x64_i8 v[58:61], v[138:141], v[182:185], v[58:61]
	v_mfma_i32_16x16x64_i8 v[54:57], v[66:69], v[190:193], v[54:57]
	v_mfma_i32_16x16x64_i8 v[50:53], v[138:141], v[190:193], v[50:53]
	v_mfma_i32_16x16x64_i8 v[46:49], v[66:69], v[206:209], v[46:49]
	v_mfma_i32_16x16x64_i8 v[42:45], v[138:141], v[206:209], v[42:45]
	v_mfma_i32_16x16x64_i8 v[38:41], v[66:69], v[224:227], v[38:41]
	v_mfma_i32_16x16x64_i8 v[34:37], v[138:141], v[224:227], v[34:37]
	v_mfma_i32_16x16x64_i8 v[62:65], v[70:73], v[186:189], v[62:65]
	v_mfma_i32_16x16x64_i8 v[58:61], v[142:145], v[186:189], v[58:61]
	v_mfma_i32_16x16x64_i8 v[54:57], v[70:73], v[202:205], v[54:57]
	v_mfma_i32_16x16x64_i8 v[50:53], v[142:145], v[202:205], v[50:53]
	v_mfma_i32_16x16x64_i8 v[46:49], v[70:73], v[210:213], v[46:49]
	v_mfma_i32_16x16x64_i8 v[42:45], v[142:145], v[210:213], v[42:45]
	v_mfma_i32_16x16x64_i8 v[38:41], v[70:73], v[228:231], v[38:41]
	v_mfma_i32_16x16x64_i8 v[34:37], v[142:145], v[228:231], v[34:37]
	v_mfma_i32_16x16x64_i8 v[30:33], v[146:149], v[182:185], v[30:33]
	v_mfma_i32_16x16x64_i8 v[26:29], v[154:157], v[182:185], v[26:29]
	v_mfma_i32_16x16x64_i8 v[22:25], v[146:149], v[190:193], v[22:25]
	v_mfma_i32_16x16x64_i8 v[18:21], v[154:157], v[190:193], v[18:21]
	v_mfma_i32_16x16x64_i8 v[14:17], v[146:149], v[206:209], v[14:17]
	v_mfma_i32_16x16x64_i8 v[10:13], v[154:157], v[206:209], v[10:13]
	v_mfma_i32_16x16x64_i8 v[6:9], v[146:149], v[224:227], v[6:9]
	v_mfma_i32_16x16x64_i8 v[2:5], v[154:157], v[224:227], v[2:5]
	v_mfma_i32_16x16x64_i8 v[30:33], v[150:153], v[186:189], v[30:33]
	v_mfma_i32_16x16x64_i8 v[26:29], v[158:161], v[186:189], v[26:29]
	v_mfma_i32_16x16x64_i8 v[22:25], v[150:153], v[202:205], v[22:25]
	v_mfma_i32_16x16x64_i8 v[18:21], v[158:161], v[202:205], v[18:21]
	v_mfma_i32_16x16x64_i8 v[14:17], v[150:153], v[210:213], v[14:17]
	v_mfma_i32_16x16x64_i8 v[10:13], v[158:161], v[210:213], v[10:13]
	v_mfma_i32_16x16x64_i8 v[6:9], v[150:153], v[228:231], v[6:9]
	v_mfma_i32_16x16x64_i8 v[2:5], v[158:161], v[228:231], v[2:5]
	s_barrier
	s_add_i32 s31, 0, 0x18000
	s_add_i32 s38, 0, 0x1c000
	v_add_u32_e32 v142, s31, v201
	v_add_u32_e32 v158, s38, v201
	ds_read_b128 v[66:69], v142
	ds_read_b128 v[70:73], v142 offset:1024
	ds_read_b128 v[138:141], v142 offset:2048
	ds_read_b128 v[142:145], v142 offset:3072
	ds_read_b128 v[146:149], v158
	ds_read_b128 v[150:153], v158 offset:1024
	ds_read_b128 v[154:157], v158 offset:2048
	ds_read_b128 v[158:161], v158 offset:3072
	s_add_u32 s36, vcc_lo, 0x40000
	s_addc_u32 s37, vcc_hi, 0
	s_mov_b32 m0, s79
	v_lshl_add_u64 v[234:235], s[36:37], 0, v[172:173]
	ds_read_b128 v[182:185], v222 offset:32768
	ds_read_b128 v[186:189], v222 offset:33792
	ds_read_b128 v[190:193], v222 offset:34816
	ds_read_b128 v[202:205], v222 offset:35840
	ds_read_b128 v[206:209], v222 offset:36864
	ds_read_b128 v[210:213], v222 offset:37888
	ds_read_b128 v[224:227], v222 offset:38912
	ds_read_b128 v[228:231], v222 offset:39936
	global_load_lds_dwordx4 v[234:235], off
	v_lshl_add_u64 v[234:235], s[36:37], 0, v[174:175]
	s_mov_b32 m0, s80
	s_nop 0
	global_load_lds_dwordx4 v[234:235], off
	s_waitcnt vmcnt(8)
	s_waitcnt lgkmcnt(0)
	s_barrier
	v_mfma_i32_16x16x64_i8 v[134:137], v[66:69], v[182:185], v[134:137]
	v_mfma_i32_16x16x64_i8 v[130:133], v[138:141], v[182:185], v[130:133]
	v_mfma_i32_16x16x64_i8 v[126:129], v[66:69], v[190:193], v[126:129]
	v_mfma_i32_16x16x64_i8 v[122:125], v[138:141], v[190:193], v[122:125]
	v_mfma_i32_16x16x64_i8 v[118:121], v[66:69], v[206:209], v[118:121]
	v_mfma_i32_16x16x64_i8 v[114:117], v[138:141], v[206:209], v[114:117]
	v_mfma_i32_16x16x64_i8 v[78:81], v[66:69], v[224:227], v[78:81]
	v_mfma_i32_16x16x64_i8 v[74:77], v[138:141], v[224:227], v[74:77]
	v_mfma_i32_16x16x64_i8 v[134:137], v[70:73], v[186:189], v[134:137]
	v_mfma_i32_16x16x64_i8 v[130:133], v[142:145], v[186:189], v[130:133]
	v_mfma_i32_16x16x64_i8 v[126:129], v[70:73], v[202:205], v[126:129]
	v_mfma_i32_16x16x64_i8 v[122:125], v[142:145], v[202:205], v[122:125]
	v_mfma_i32_16x16x64_i8 v[118:121], v[70:73], v[210:213], v[118:121]
	v_mfma_i32_16x16x64_i8 v[114:117], v[142:145], v[210:213], v[114:117]
	v_mfma_i32_16x16x64_i8 v[78:81], v[70:73], v[228:231], v[78:81]
	v_mfma_i32_16x16x64_i8 v[74:77], v[142:145], v[228:231], v[74:77]
	v_mfma_i32_16x16x64_i8 v[110:113], v[146:149], v[182:185], v[110:113]
	v_mfma_i32_16x16x64_i8 v[106:109], v[154:157], v[182:185], v[106:109]
	v_mfma_i32_16x16x64_i8 v[102:105], v[146:149], v[190:193], v[102:105]
	v_mfma_i32_16x16x64_i8 v[98:101], v[154:157], v[190:193], v[98:101]
	v_mfma_i32_16x16x64_i8 v[94:97], v[146:149], v[206:209], v[94:97]
	v_mfma_i32_16x16x64_i8 v[90:93], v[154:157], v[206:209], v[90:93]
	v_mfma_i32_16x16x64_i8 v[86:89], v[146:149], v[224:227], v[86:89]
	v_mfma_i32_16x16x64_i8 v[82:85], v[154:157], v[224:227], v[82:85]
	v_mfma_i32_16x16x64_i8 v[110:113], v[150:153], v[186:189], v[110:113]
	v_mfma_i32_16x16x64_i8 v[106:109], v[158:161], v[186:189], v[106:109]
	v_mfma_i32_16x16x64_i8 v[102:105], v[150:153], v[202:205], v[102:105]
	v_mfma_i32_16x16x64_i8 v[98:101], v[158:161], v[202:205], v[98:101]
	v_mfma_i32_16x16x64_i8 v[94:97], v[150:153], v[210:213], v[94:97]
	v_mfma_i32_16x16x64_i8 v[90:93], v[158:161], v[210:213], v[90:93]
	v_mfma_i32_16x16x64_i8 v[86:89], v[150:153], v[228:231], v[86:89]
	v_mfma_i32_16x16x64_i8 v[82:85], v[158:161], v[228:231], v[82:85]
	s_barrier
	s_add_i32 s31, s31, s61
	v_lshl_add_u64 v[168:169], v[168:169], 0, s[44:45]
	s_mov_b32 m0, s31
	ds_read_b128 v[182:185], v222 offset:49152
	ds_read_b128 v[186:189], v222 offset:50176
	ds_read_b128 v[190:193], v222 offset:51200
	ds_read_b128 v[202:205], v222 offset:52224
	ds_read_b128 v[206:209], v222 offset:53248
	ds_read_b128 v[210:213], v222 offset:54272
	ds_read_b128 v[224:227], v222 offset:55296
	ds_read_b128 v[228:231], v222 offset:56320
	global_load_lds_dwordx4 v[168:169], off
	s_add_i32 m0, s31, 0x2000
	s_add_u32 s36, s66, 0x90080
	v_lshl_add_u64 v[168:169], v[170:171], 0, s[44:45]
	s_addc_u32 s37, s67, 0
	s_add_i32 s31, s38, s61
	global_load_lds_dwordx4 v[168:169], off
	v_lshl_add_u64 v[168:169], s[36:37], 0, v[162:163]
	s_mov_b32 m0, s31
	s_nop 0
	global_load_lds_dwordx4 v[168:169], off
	v_lshl_add_u64 v[168:169], s[36:37], 0, v[176:177]
	s_add_i32 m0, s31, 0x2000
	s_nop 0
	global_load_lds_dwordx4 v[168:169], off
	v_lshl_add_u64 v[168:169], v[214:215], 0, s[44:45]
	s_mov_b32 m0, s82
	s_nop 0
	global_load_lds_dwordx4 v[168:169], off
	v_lshl_add_u64 v[168:169], v[232:233], 0, s[44:45]
	s_mov_b32 m0, s83
	s_nop 0
	global_load_lds_dwordx4 v[168:169], off
	s_waitcnt vmcnt(8)
	s_waitcnt lgkmcnt(0)
	s_barrier
	v_mfma_i32_16x16x64_i8 v[62:65], v[66:69], v[182:185], v[62:65]
	v_mfma_i32_16x16x64_i8 v[58:61], v[138:141], v[182:185], v[58:61]
	s_add_i32 s27, s27, 2
	v_mfma_i32_16x16x64_i8 v[54:57], v[66:69], v[190:193], v[54:57]
	s_add_u32 s25, s25, 0x100
	v_mfma_i32_16x16x64_i8 v[50:53], v[138:141], v[190:193], v[50:53]
	s_addc_u32 s26, s26, 0
	v_mfma_i32_16x16x64_i8 v[46:49], v[66:69], v[206:209], v[46:49]
	s_add_u32 s64, s64, 0x100
	v_mfma_i32_16x16x64_i8 v[42:45], v[138:141], v[206:209], v[42:45]
	s_addc_u32 s65, s65, 0
	v_mfma_i32_16x16x64_i8 v[38:41], v[66:69], v[224:227], v[38:41]
	s_cmp_gt_u32 s27, 13
	v_mfma_i32_16x16x64_i8 v[34:37], v[138:141], v[224:227], v[34:37]
	v_mfma_i32_16x16x64_i8 v[62:65], v[70:73], v[186:189], v[62:65]
	v_mfma_i32_16x16x64_i8 v[58:61], v[142:145], v[186:189], v[58:61]
	v_mfma_i32_16x16x64_i8 v[54:57], v[70:73], v[202:205], v[54:57]
	v_mfma_i32_16x16x64_i8 v[50:53], v[142:145], v[202:205], v[50:53]
	v_mfma_i32_16x16x64_i8 v[46:49], v[70:73], v[210:213], v[46:49]
	v_mfma_i32_16x16x64_i8 v[42:45], v[142:145], v[210:213], v[42:45]
	v_mfma_i32_16x16x64_i8 v[38:41], v[70:73], v[228:231], v[38:41]
	v_mfma_i32_16x16x64_i8 v[34:37], v[142:145], v[228:231], v[34:37]
	v_mfma_i32_16x16x64_i8 v[30:33], v[146:149], v[182:185], v[30:33]
	v_mfma_i32_16x16x64_i8 v[26:29], v[154:157], v[182:185], v[26:29]
	v_mfma_i32_16x16x64_i8 v[22:25], v[146:149], v[190:193], v[22:25]
	v_mfma_i32_16x16x64_i8 v[18:21], v[154:157], v[190:193], v[18:21]
	v_mfma_i32_16x16x64_i8 v[14:17], v[146:149], v[206:209], v[14:17]
	v_mfma_i32_16x16x64_i8 v[10:13], v[154:157], v[206:209], v[10:13]
	v_mfma_i32_16x16x64_i8 v[6:9], v[146:149], v[224:227], v[6:9]
	v_mfma_i32_16x16x64_i8 v[2:5], v[154:157], v[224:227], v[2:5]
	v_mfma_i32_16x16x64_i8 v[30:33], v[150:153], v[186:189], v[30:33]
	v_mfma_i32_16x16x64_i8 v[26:29], v[158:161], v[186:189], v[26:29]
	v_mfma_i32_16x16x64_i8 v[22:25], v[150:153], v[202:205], v[22:25]
	v_mfma_i32_16x16x64_i8 v[18:21], v[158:161], v[202:205], v[18:21]
	v_mfma_i32_16x16x64_i8 v[14:17], v[150:153], v[210:213], v[14:17]
	v_mfma_i32_16x16x64_i8 v[10:13], v[158:161], v[210:213], v[10:13]
	v_mfma_i32_16x16x64_i8 v[6:9], v[150:153], v[228:231], v[6:9]
	v_mfma_i32_16x16x64_i8 v[2:5], v[158:161], v[228:231], v[2:5]
	s_barrier
	s_cbranch_scc0 .LBB0_1615
	s_and_b64 vcc, exec, s[22:23]
	s_cbranch_vccz .LBB0_1618
	s_barrier
